# cross-attention QK section hand-pipelined: Q fragments resident, 7-deep K fragment ring
# baseline (speedup 1.0000x reference)
.LBB0_707:
	s_ashr_i32 s16, s53, 3
	v_mov_b32_e32 v230, v232
	s_ashr_i32 s17, s16, 31
	v_readfirstlane_b32 s4, v230
	s_lshl_b32 s5, s53, 8
	s_ashr_i32 s4, s4, 6
	s_lshl_b64 s[18:19], s[16:17], 11
	s_and_b32 s5, s5, 0x700
	v_and_b32_e32 v234, 31, v230
	s_or_b32 s5, s18, s5
	s_lshl_b32 s18, s4, 5
	s_lshl_b64 s[16:17], s[16:17], 20
	v_or_b32_e32 v2, s5, v234
	s_add_u32 s5, s22, s16
	v_mov_b32_e32 v3, s19
	s_addc_u32 s19, s23, s17
	s_lshl_b32 s16, s52, 8
	v_bfe_u32 v231, v230, 5, 1
	s_ashr_i32 s17, s16, 31
	v_lshrrev_b32_e32 v6, 5, v230
	s_lshl_b64 s[16:17], s[16:17], 1
	v_or_b32_e32 v4, s18, v231
	s_add_u32 s20, s5, s16
	v_bitop3_b32 v0, v6, v230, 1 bitop3:0x6c
	v_ashrrev_i32_e32 v5, 31, v4
	s_addc_u32 s21, s19, s17
	s_lshl_b32 s19, s4, 4
	v_lshlrev_b64 v[4:5], 12, v[4:5]
	v_lshlrev_b32_e32 v0, 4, v0
	v_lshl_add_u64 v[156:157], s[20:21], 0, v[4:5]
	v_and_b32_e32 v0, 0x1f0, v0
	s_lshl_b32 s4, s19, 10
	s_barrier
	v_lshl_add_u64 v[4:5], v[156:157], 0, v[0:1]
	s_add_i32 s24, s4, 0
	s_mov_b32 s4, m0
	s_mov_b32 m0, s24
	s_nop 0
	global_load_lds_dwordx4 v[4:5], off
	s_mov_b32 m0, s4
	s_or_b32 s4, s19, 1
	s_lshl_b32 s5, s4, 1
	v_or_b32_e32 v158, s5, v231
	v_bitop3_b32 v0, s5, v230, v231 bitop3:0x36
	v_ashrrev_i32_e32 v159, 31, v158
	v_lshlrev_b64 v[4:5], 12, v[158:159]
	v_lshlrev_b32_e32 v0, 4, v0
	v_lshl_add_u64 v[160:161], s[20:21], 0, v[4:5]
	v_and_b32_e32 v0, 0x1f0, v0
	s_lshl_b32 s4, s4, 10
	v_lshl_add_u64 v[4:5], v[160:161], 0, v[0:1]
	s_add_i32 s25, s4, 0
	s_mov_b32 s4, m0
	s_mov_b32 m0, s25
	s_nop 0
	global_load_lds_dwordx4 v[4:5], off
	s_mov_b32 m0, s4
	s_or_b32 s4, s19, 2
	s_lshl_b32 s5, s4, 1
	v_or_b32_e32 v162, s5, v231
	v_bitop3_b32 v0, s5, v230, v231 bitop3:0x36
	v_ashrrev_i32_e32 v163, 31, v162
	v_lshlrev_b64 v[4:5], 12, v[162:163]
	v_lshlrev_b32_e32 v0, 4, v0
	v_lshl_add_u64 v[164:165], s[20:21], 0, v[4:5]
	v_and_b32_e32 v0, 0x1f0, v0
	s_lshl_b32 s4, s4, 10
	v_lshl_add_u64 v[4:5], v[164:165], 0, v[0:1]
	s_add_i32 s26, s4, 0
	s_mov_b32 s4, m0
	s_mov_b32 m0, s26
	s_nop 0
	global_load_lds_dwordx4 v[4:5], off
	s_mov_b32 m0, s4
	s_or_b32 s4, s19, 3
	s_lshl_b32 s5, s4, 1
	v_or_b32_e32 v166, s5, v231
	v_bitop3_b32 v0, s5, v230, v231 bitop3:0x36
	v_ashrrev_i32_e32 v167, 31, v166
	v_lshlrev_b64 v[4:5], 12, v[166:167]
	v_lshlrev_b32_e32 v0, 4, v0
	v_lshl_add_u64 v[168:169], s[20:21], 0, v[4:5]
	v_and_b32_e32 v0, 0x1f0, v0
	s_lshl_b32 s4, s4, 10
	v_lshl_add_u64 v[4:5], v[168:169], 0, v[0:1]
	s_add_i32 s27, s4, 0
	s_mov_b32 s4, m0
	s_mov_b32 m0, s27
	s_nop 0
	global_load_lds_dwordx4 v[4:5], off
	s_mov_b32 m0, s4
	s_or_b32 s4, s19, 4
	s_lshl_b32 s5, s4, 1
	v_or_b32_e32 v170, s5, v231
	v_bitop3_b32 v0, s5, v230, v231 bitop3:0x36
	v_ashrrev_i32_e32 v171, 31, v170
	v_lshlrev_b64 v[4:5], 12, v[170:171]
	v_lshlrev_b32_e32 v0, 4, v0
	v_lshl_add_u64 v[172:173], s[20:21], 0, v[4:5]
	v_and_b32_e32 v0, 0x1f0, v0
	s_lshl_b32 s4, s4, 10
	v_lshl_add_u64 v[4:5], v[172:173], 0, v[0:1]
	s_add_i32 s28, s4, 0
	s_mov_b32 s4, m0
	s_mov_b32 m0, s28
	s_nop 0
	global_load_lds_dwordx4 v[4:5], off
	s_mov_b32 m0, s4
	s_or_b32 s4, s19, 5
	s_lshl_b32 s5, s4, 1
	v_or_b32_e32 v174, s5, v231
	v_bitop3_b32 v0, s5, v230, v231 bitop3:0x36
	v_ashrrev_i32_e32 v175, 31, v174
	v_lshlrev_b64 v[4:5], 12, v[174:175]
	v_lshlrev_b32_e32 v0, 4, v0
	v_lshl_add_u64 v[176:177], s[20:21], 0, v[4:5]
	v_and_b32_e32 v0, 0x1f0, v0
	s_lshl_b32 s4, s4, 10
	v_lshl_add_u64 v[4:5], v[176:177], 0, v[0:1]
	s_add_i32 s29, s4, 0
	s_mov_b32 s4, m0
	s_mov_b32 m0, s29
	s_nop 0
	global_load_lds_dwordx4 v[4:5], off
	s_mov_b32 m0, s4
	s_or_b32 s4, s19, 6
	s_lshl_b32 s5, s4, 1
	v_or_b32_e32 v178, s5, v231
	v_bitop3_b32 v0, s5, v230, v231 bitop3:0x36
	v_ashrrev_i32_e32 v179, 31, v178
	v_lshlrev_b64 v[4:5], 12, v[178:179]
	v_lshlrev_b32_e32 v0, 4, v0
	v_lshl_add_u64 v[180:181], s[20:21], 0, v[4:5]
	v_and_b32_e32 v0, 0x1f0, v0
	s_lshl_b32 s4, s4, 10
	v_lshl_add_u64 v[4:5], v[180:181], 0, v[0:1]
	s_add_i32 s30, s4, 0
	s_mov_b32 s4, m0
	s_mov_b32 m0, s30
	s_nop 0
	global_load_lds_dwordx4 v[4:5], off
	s_mov_b32 m0, s4
	s_or_b32 s4, s19, 7
	s_lshl_b32 s5, s4, 1
	v_or_b32_e32 v182, s5, v231
	v_bitop3_b32 v0, s5, v230, v231 bitop3:0x36
	v_ashrrev_i32_e32 v183, 31, v182
	v_lshlrev_b64 v[4:5], 12, v[182:183]
	v_lshlrev_b32_e32 v0, 4, v0
	v_lshl_add_u64 v[184:185], s[20:21], 0, v[4:5]
	v_and_b32_e32 v0, 0x1f0, v0
	s_lshl_b32 s4, s4, 10
	v_lshl_add_u64 v[4:5], v[184:185], 0, v[0:1]
	s_add_i32 s31, s4, 0
	s_mov_b32 s4, m0
	s_mov_b32 m0, s31
	s_nop 0
	global_load_lds_dwordx4 v[4:5], off
	s_mov_b32 m0, s4
	s_or_b32 s4, s19, 8
	s_lshl_b32 s5, s4, 1
	v_or_b32_e32 v186, s5, v231
	v_bitop3_b32 v0, s5, v230, v231 bitop3:0x36
	v_ashrrev_i32_e32 v187, 31, v186
	v_lshlrev_b64 v[4:5], 12, v[186:187]
	v_lshlrev_b32_e32 v0, 4, v0
	v_lshl_add_u64 v[188:189], s[20:21], 0, v[4:5]
	v_and_b32_e32 v0, 0x1f0, v0
	s_lshl_b32 s4, s4, 10
	v_lshl_add_u64 v[4:5], v[188:189], 0, v[0:1]
	s_add_i32 s34, s4, 0
	s_mov_b32 s4, m0
	s_mov_b32 m0, s34
	s_nop 0
	global_load_lds_dwordx4 v[4:5], off
	s_mov_b32 m0, s4
	s_or_b32 s4, s19, 9
	s_lshl_b32 s5, s4, 1
	v_or_b32_e32 v190, s5, v231
	v_bitop3_b32 v0, s5, v230, v231 bitop3:0x36
	v_ashrrev_i32_e32 v191, 31, v190
	v_lshlrev_b64 v[4:5], 12, v[190:191]
	v_lshlrev_b32_e32 v0, 4, v0
	v_lshl_add_u64 v[192:193], s[20:21], 0, v[4:5]
	v_and_b32_e32 v0, 0x1f0, v0
	s_lshl_b32 s4, s4, 10
	v_lshl_add_u64 v[4:5], v[192:193], 0, v[0:1]
	s_add_i32 s35, s4, 0
	s_mov_b32 s4, m0
	s_mov_b32 m0, s35
	s_nop 0
	global_load_lds_dwordx4 v[4:5], off
	s_mov_b32 m0, s4
	s_or_b32 s4, s19, 10
	s_lshl_b32 s5, s4, 1
	v_or_b32_e32 v202, s5, v231
	v_bitop3_b32 v0, s5, v230, v231 bitop3:0x36
	v_ashrrev_i32_e32 v203, 31, v202
	v_lshlrev_b64 v[4:5], 12, v[202:203]
	v_lshlrev_b32_e32 v0, 4, v0
	v_lshl_add_u64 v[204:205], s[20:21], 0, v[4:5]
	v_and_b32_e32 v0, 0x1f0, v0
	s_lshl_b32 s4, s4, 10
	v_lshl_add_u64 v[4:5], v[204:205], 0, v[0:1]
	s_add_i32 s36, s4, 0
	s_mov_b32 s4, m0
	s_mov_b32 m0, s36
	s_nop 0
	global_load_lds_dwordx4 v[4:5], off
	s_mov_b32 m0, s4
	s_or_b32 s4, s19, 11
	s_lshl_b32 s5, s4, 1
	v_or_b32_e32 v206, s5, v231
	v_bitop3_b32 v0, s5, v230, v231 bitop3:0x36
	v_ashrrev_i32_e32 v207, 31, v206
	v_lshlrev_b64 v[4:5], 12, v[206:207]
	v_lshlrev_b32_e32 v0, 4, v0
	v_lshl_add_u64 v[208:209], s[20:21], 0, v[4:5]
	v_and_b32_e32 v0, 0x1f0, v0
	s_lshl_b32 s4, s4, 10
	v_lshl_add_u64 v[4:5], v[208:209], 0, v[0:1]
	s_add_i32 s37, s4, 0
	s_mov_b32 s4, m0
	s_mov_b32 m0, s37
	s_nop 0
	global_load_lds_dwordx4 v[4:5], off
	s_mov_b32 m0, s4
	s_or_b32 s4, s19, 12
	s_lshl_b32 s5, s4, 1
	v_or_b32_e32 v210, s5, v231
	v_bitop3_b32 v0, s5, v230, v231 bitop3:0x36
	v_ashrrev_i32_e32 v211, 31, v210
	v_lshlrev_b64 v[4:5], 12, v[210:211]
	v_lshlrev_b32_e32 v0, 4, v0
	v_lshl_add_u64 v[212:213], s[20:21], 0, v[4:5]
	v_and_b32_e32 v0, 0x1f0, v0
	s_lshl_b32 s4, s4, 10
	v_lshl_add_u64 v[4:5], v[212:213], 0, v[0:1]
	s_add_i32 s38, s4, 0
	s_mov_b32 s4, m0
	s_mov_b32 m0, s38
	s_nop 0
	global_load_lds_dwordx4 v[4:5], off
	s_mov_b32 m0, s4
	s_or_b32 s4, s19, 13
	s_lshl_b32 s5, s4, 1
	v_or_b32_e32 v214, s5, v231
	v_bitop3_b32 v0, s5, v230, v231 bitop3:0x36
	v_ashrrev_i32_e32 v215, 31, v214
	v_lshlrev_b64 v[4:5], 12, v[214:215]
	v_lshlrev_b32_e32 v0, 4, v0
	v_lshl_add_u64 v[216:217], s[20:21], 0, v[4:5]
	v_and_b32_e32 v0, 0x1f0, v0
	s_lshl_b32 s4, s4, 10
	v_lshl_add_u64 v[4:5], v[216:217], 0, v[0:1]
	s_add_i32 s39, s4, 0
	s_mov_b32 s4, m0
	s_mov_b32 m0, s39
	s_nop 0
	global_load_lds_dwordx4 v[4:5], off
	s_mov_b32 m0, s4
	s_or_b32 s4, s19, 14
	s_lshl_b32 s5, s4, 1
	v_or_b32_e32 v218, s5, v231
	v_bitop3_b32 v0, s5, v230, v231 bitop3:0x36
	v_ashrrev_i32_e32 v219, 31, v218
	v_lshlrev_b64 v[4:5], 12, v[218:219]
	v_lshlrev_b32_e32 v0, 4, v0
	v_lshl_add_u64 v[220:221], s[20:21], 0, v[4:5]
	v_and_b32_e32 v0, 0x1f0, v0
	s_lshl_b32 s4, s4, 10
	v_lshl_add_u64 v[4:5], v[220:221], 0, v[0:1]
	s_add_i32 s40, s4, 0
	s_mov_b32 s4, m0
	s_mov_b32 m0, s40
	s_nop 0
	global_load_lds_dwordx4 v[4:5], off
	s_mov_b32 m0, s4
	s_or_b32 s4, s19, 15
	s_lshl_b32 s5, s4, 1
	v_or_b32_e32 v222, s5, v231
	v_bitop3_b32 v0, s5, v230, v231 bitop3:0x36
	v_ashrrev_i32_e32 v223, 31, v222
	s_ashr_i32 s19, s18, 31
	v_lshlrev_b64 v[4:5], 12, v[222:223]
	v_lshlrev_b32_e32 v0, 4, v0
	v_lshl_add_u64 v[226:227], v[2:3], 0, s[18:19]
	v_lshl_add_u64 v[224:225], s[20:21], 0, v[4:5]
	v_and_b32_e32 v0, 0x1f0, v0
	v_lshlrev_b64 v[154:155], 11, v[226:227]
	v_lshl_add_u64 v[4:5], v[224:225], 0, v[0:1]
	s_lshl_b32 s4, s4, 10
	v_lshl_add_u64 v[2:3], s[8:9], 0, v[154:155]
	s_add_i32 s20, s4, 0
	s_mov_b32 s4, m0
	s_mov_b32 m0, s20
	s_nop 0
	global_load_lds_dwordx4 v[4:5], off
	s_mov_b32 m0, s4
	v_lshl_add_u64 v[2:3], v[2:3], 0, s[16:17]
	v_lshlrev_b32_e32 v4, 4, v231
	v_mov_b32_e32 v5, v1
	v_lshl_add_u64 v[228:229], v[2:3], 0, v[4:5]
	v_mov_b64_e32 v[252:253], v[156:157]
	global_load_dwordx4 v[156:159], v[228:229], off
	global_load_dwordx4 v[160:163], v[228:229], off offset:32
	global_load_dwordx4 v[164:167], v[228:229], off offset:64
	global_load_dwordx4 v[168:171], v[228:229], off offset:96
	global_load_dwordx4 v[172:175], v[228:229], off offset:128
	global_load_dwordx4 v[176:179], v[228:229], off offset:160
	global_load_dwordx4 v[180:183], v[228:229], off offset:192
	global_load_dwordx4 v[184:187], v[228:229], off offset:224
	global_load_dwordx4 v[188:191], v[228:229], off offset:256
	global_load_dwordx4 v[192:195], v[228:229], off offset:288
	global_load_dwordx4 v[130:133], v[228:229], off offset:320
	global_load_dwordx4 v[134:137], v[228:229], off offset:352
	global_load_dwordx4 v[138:141], v[228:229], off offset:384
	global_load_dwordx4 v[142:145], v[228:229], off offset:416
	global_load_dwordx4 v[146:149], v[228:229], off offset:448
	global_load_dwordx4 v[150:153], v[228:229], off offset:480
	s_lshl_b32 s18, s52, 2
	s_ashr_i32 s19, s18, 31
	v_lshlrev_b64 v[242:243], 6, v[226:227]
	v_lshl_add_u64 v[242:243], s[10:11], 0, v[242:243]
	v_lshl_add_u64 v[242:243], s[18:19], 2, v[242:243]
	global_load_dwordx4 v[242:245], v[242:243], off
	v_lshlrev_b32_e32 v198, 9, v234
	s_waitcnt vmcnt(0)
	s_barrier
	v_add_f32_e32 v235, v243, v242
	v_add_f32_e32 v236, v244, v245
	v_add_f32_e32 v235, v235, v236
	v_fmamk_f32 v235, v235, 0x3b800000, v233
	v_cmp_gt_f32_e32 vcc, s82, v235
	v_mul_f32_e32 v236, 0x4b800000, v235
	s_nop 0
	v_cndmask_b32_e32 v235, v235, v236, vcc
	v_rsq_f32_e32 v235, v235
	s_nop 0
	v_mul_f32_e32 v236, 0x45800000, v235
	v_cndmask_b32_e32 v254, v235, v236, vcc
	v_bitop3_b32 v237, v231, v234, 0 bitop3:0x36
	v_lshlrev_b32_e32 v237, 4, v237
	v_add3_u32 v235, 0, v237, v198
	v_add_u32_e32 v236, 0x10000, v235
	ds_read_b128 v[202:205], v235
	ds_read_b128 v[206:209], v235 offset:16384
	ds_read_b128 v[210:213], v235 offset:32768
	ds_read_b128 v[214:217], v235 offset:49152
	ds_read_b128 v[218:221], v236
	ds_read_b128 v[222:225], v236 offset:16384
	ds_read_b128 v[242:245], v236 offset:32768
	s_waitcnt lgkmcnt(6)
	v_mfma_f32_32x32x16_bf16 v[66:81], v[202:205], v[156:159], 0
	ds_read_b128 v[202:205], v236 offset:49152
	s_waitcnt lgkmcnt(6)
	v_mfma_f32_32x32x16_bf16 v[82:97], v[206:209], v[156:159], 0
	v_bitop3_b32 v237, v231, v234, 2 bitop3:0x36
	v_lshlrev_b32_e32 v237, 4, v237
	v_add3_u32 v235, 0, v237, v198
	v_add_u32_e32 v236, 0x10000, v235
	ds_read_b128 v[206:209], v235
	s_waitcnt lgkmcnt(6)
	v_mfma_f32_32x32x16_bf16 v[98:113], v[210:213], v[156:159], 0
	ds_read_b128 v[210:213], v235 offset:16384
	s_waitcnt lgkmcnt(6)
	v_mfma_f32_32x32x16_bf16 v[114:129], v[214:217], v[156:159], 0
	ds_read_b128 v[214:217], v235 offset:32768
	s_waitcnt lgkmcnt(6)
	v_mfma_f32_32x32x16_bf16 v[2:17], v[218:221], v[156:159], 0
	ds_read_b128 v[218:221], v235 offset:49152
	s_waitcnt lgkmcnt(6)
	v_mfma_f32_32x32x16_bf16 v[50:65], v[222:225], v[156:159], 0
	ds_read_b128 v[222:225], v236
	s_waitcnt lgkmcnt(6)
	v_mfma_f32_32x32x16_bf16 v[34:49], v[242:245], v[156:159], 0
	ds_read_b128 v[242:245], v236 offset:16384
	s_waitcnt lgkmcnt(6)
	v_mfma_f32_32x32x16_bf16 v[18:33], v[202:205], v[156:159], 0
	ds_read_b128 v[202:205], v236 offset:32768
	s_waitcnt lgkmcnt(6)
	v_mfma_f32_32x32x16_bf16 v[66:81], v[206:209], v[160:163], v[66:81]
	ds_read_b128 v[206:209], v236 offset:49152
	s_waitcnt lgkmcnt(6)
	v_mfma_f32_32x32x16_bf16 v[82:97], v[210:213], v[160:163], v[82:97]
	v_bitop3_b32 v237, v231, v234, 4 bitop3:0x36
	v_lshlrev_b32_e32 v237, 4, v237
	v_add3_u32 v235, 0, v237, v198
	v_add_u32_e32 v236, 0x10000, v235
	ds_read_b128 v[210:213], v235
	s_waitcnt lgkmcnt(6)
	v_mfma_f32_32x32x16_bf16 v[98:113], v[214:217], v[160:163], v[98:113]
	ds_read_b128 v[214:217], v235 offset:16384
	s_waitcnt lgkmcnt(6)
	v_mfma_f32_32x32x16_bf16 v[114:129], v[218:221], v[160:163], v[114:129]
	ds_read_b128 v[218:221], v235 offset:32768
	s_waitcnt lgkmcnt(6)
	v_mfma_f32_32x32x16_bf16 v[2:17], v[222:225], v[160:163], v[2:17]
	ds_read_b128 v[222:225], v235 offset:49152
	s_waitcnt lgkmcnt(6)
	v_mfma_f32_32x32x16_bf16 v[50:65], v[242:245], v[160:163], v[50:65]
	ds_read_b128 v[242:245], v236
	s_waitcnt lgkmcnt(6)
	v_mfma_f32_32x32x16_bf16 v[34:49], v[202:205], v[160:163], v[34:49]
	ds_read_b128 v[202:205], v236 offset:16384
	s_waitcnt lgkmcnt(6)
	v_mfma_f32_32x32x16_bf16 v[18:33], v[206:209], v[160:163], v[18:33]
	ds_read_b128 v[206:209], v236 offset:32768
	s_waitcnt lgkmcnt(6)
	v_mfma_f32_32x32x16_bf16 v[66:81], v[210:213], v[164:167], v[66:81]
	ds_read_b128 v[210:213], v236 offset:49152
	s_waitcnt lgkmcnt(6)
	v_mfma_f32_32x32x16_bf16 v[82:97], v[214:217], v[164:167], v[82:97]
	v_bitop3_b32 v237, v231, v234, 6 bitop3:0x36
	v_lshlrev_b32_e32 v237, 4, v237
	v_add3_u32 v235, 0, v237, v198
	v_add_u32_e32 v236, 0x10000, v235
	ds_read_b128 v[214:217], v235
	s_waitcnt lgkmcnt(6)
	v_mfma_f32_32x32x16_bf16 v[98:113], v[218:221], v[164:167], v[98:113]
	ds_read_b128 v[218:221], v235 offset:16384
	s_waitcnt lgkmcnt(6)
	v_mfma_f32_32x32x16_bf16 v[114:129], v[222:225], v[164:167], v[114:129]
	ds_read_b128 v[222:225], v235 offset:32768
	s_waitcnt lgkmcnt(6)
	v_mfma_f32_32x32x16_bf16 v[2:17], v[242:245], v[164:167], v[2:17]
	ds_read_b128 v[242:245], v235 offset:49152
	s_waitcnt lgkmcnt(6)
	v_mfma_f32_32x32x16_bf16 v[50:65], v[202:205], v[164:167], v[50:65]
	ds_read_b128 v[202:205], v236
	s_waitcnt lgkmcnt(6)
	v_mfma_f32_32x32x16_bf16 v[34:49], v[206:209], v[164:167], v[34:49]
	ds_read_b128 v[206:209], v236 offset:16384
	s_waitcnt lgkmcnt(6)
	v_mfma_f32_32x32x16_bf16 v[18:33], v[210:213], v[164:167], v[18:33]
	ds_read_b128 v[210:213], v236 offset:32768
	s_waitcnt lgkmcnt(6)
	v_mfma_f32_32x32x16_bf16 v[66:81], v[214:217], v[168:171], v[66:81]
	ds_read_b128 v[214:217], v236 offset:49152
	s_waitcnt lgkmcnt(6)
	v_mfma_f32_32x32x16_bf16 v[82:97], v[218:221], v[168:171], v[82:97]
	v_bitop3_b32 v237, v231, v234, 8 bitop3:0x36
	v_lshlrev_b32_e32 v237, 4, v237
	v_add3_u32 v235, 0, v237, v198
	v_add_u32_e32 v236, 0x10000, v235
	ds_read_b128 v[218:221], v235
	s_waitcnt lgkmcnt(6)
	v_mfma_f32_32x32x16_bf16 v[98:113], v[222:225], v[168:171], v[98:113]
	ds_read_b128 v[222:225], v235 offset:16384
	s_waitcnt lgkmcnt(6)
	v_mfma_f32_32x32x16_bf16 v[114:129], v[242:245], v[168:171], v[114:129]
	ds_read_b128 v[242:245], v235 offset:32768
	s_waitcnt lgkmcnt(6)
	v_mfma_f32_32x32x16_bf16 v[2:17], v[202:205], v[168:171], v[2:17]
	ds_read_b128 v[202:205], v235 offset:49152
	s_waitcnt lgkmcnt(6)
	v_mfma_f32_32x32x16_bf16 v[50:65], v[206:209], v[168:171], v[50:65]
	ds_read_b128 v[206:209], v236
	s_waitcnt lgkmcnt(6)
	v_mfma_f32_32x32x16_bf16 v[34:49], v[210:213], v[168:171], v[34:49]
	ds_read_b128 v[210:213], v236 offset:16384
	s_waitcnt lgkmcnt(6)
	v_mfma_f32_32x32x16_bf16 v[18:33], v[214:217], v[168:171], v[18:33]
	ds_read_b128 v[214:217], v236 offset:32768
	s_waitcnt lgkmcnt(6)
	v_mfma_f32_32x32x16_bf16 v[66:81], v[218:221], v[172:175], v[66:81]
	ds_read_b128 v[218:221], v236 offset:49152
	s_waitcnt lgkmcnt(6)
	v_mfma_f32_32x32x16_bf16 v[82:97], v[222:225], v[172:175], v[82:97]
	v_bitop3_b32 v237, v231, v234, 10 bitop3:0x36
	v_lshlrev_b32_e32 v237, 4, v237
	v_add3_u32 v235, 0, v237, v198
	v_add_u32_e32 v236, 0x10000, v235
	ds_read_b128 v[222:225], v235
	s_waitcnt lgkmcnt(6)
	v_mfma_f32_32x32x16_bf16 v[98:113], v[242:245], v[172:175], v[98:113]
	ds_read_b128 v[242:245], v235 offset:16384
	s_waitcnt lgkmcnt(6)
	v_mfma_f32_32x32x16_bf16 v[114:129], v[202:205], v[172:175], v[114:129]
	ds_read_b128 v[202:205], v235 offset:32768
	s_waitcnt lgkmcnt(6)
	v_mfma_f32_32x32x16_bf16 v[2:17], v[206:209], v[172:175], v[2:17]
	ds_read_b128 v[206:209], v235 offset:49152
	s_waitcnt lgkmcnt(6)
	v_mfma_f32_32x32x16_bf16 v[50:65], v[210:213], v[172:175], v[50:65]
	ds_read_b128 v[210:213], v236
	s_waitcnt lgkmcnt(6)
	v_mfma_f32_32x32x16_bf16 v[34:49], v[214:217], v[172:175], v[34:49]
	ds_read_b128 v[214:217], v236 offset:16384
	s_waitcnt lgkmcnt(6)
	v_mfma_f32_32x32x16_bf16 v[18:33], v[218:221], v[172:175], v[18:33]
	ds_read_b128 v[218:221], v236 offset:32768
	s_waitcnt lgkmcnt(6)
	v_mfma_f32_32x32x16_bf16 v[66:81], v[222:225], v[176:179], v[66:81]
	ds_read_b128 v[222:225], v236 offset:49152
	s_waitcnt lgkmcnt(6)
	v_mfma_f32_32x32x16_bf16 v[82:97], v[242:245], v[176:179], v[82:97]
	v_bitop3_b32 v237, v231, v234, 12 bitop3:0x36
	v_lshlrev_b32_e32 v237, 4, v237
	v_add3_u32 v235, 0, v237, v198
	v_add_u32_e32 v236, 0x10000, v235
	ds_read_b128 v[242:245], v235
	s_waitcnt lgkmcnt(6)
	v_mfma_f32_32x32x16_bf16 v[98:113], v[202:205], v[176:179], v[98:113]
	ds_read_b128 v[202:205], v235 offset:16384
	s_waitcnt lgkmcnt(6)
	v_mfma_f32_32x32x16_bf16 v[114:129], v[206:209], v[176:179], v[114:129]
	ds_read_b128 v[206:209], v235 offset:32768
	s_waitcnt lgkmcnt(6)
	v_mfma_f32_32x32x16_bf16 v[2:17], v[210:213], v[176:179], v[2:17]
	ds_read_b128 v[210:213], v235 offset:49152
	s_waitcnt lgkmcnt(6)
	v_mfma_f32_32x32x16_bf16 v[50:65], v[214:217], v[176:179], v[50:65]
	ds_read_b128 v[214:217], v236
	s_waitcnt lgkmcnt(6)
	v_mfma_f32_32x32x16_bf16 v[34:49], v[218:221], v[176:179], v[34:49]
	ds_read_b128 v[218:221], v236 offset:16384
	s_waitcnt lgkmcnt(6)
	v_mfma_f32_32x32x16_bf16 v[18:33], v[222:225], v[176:179], v[18:33]
	ds_read_b128 v[222:225], v236 offset:32768
	s_waitcnt lgkmcnt(6)
	v_mfma_f32_32x32x16_bf16 v[66:81], v[242:245], v[180:183], v[66:81]
	ds_read_b128 v[242:245], v236 offset:49152
	s_waitcnt lgkmcnt(6)
	v_mfma_f32_32x32x16_bf16 v[82:97], v[202:205], v[180:183], v[82:97]
	v_bitop3_b32 v237, v231, v234, 14 bitop3:0x36
	v_lshlrev_b32_e32 v237, 4, v237
	v_add3_u32 v235, 0, v237, v198
	v_add_u32_e32 v236, 0x10000, v235
	ds_read_b128 v[202:205], v235
	s_waitcnt lgkmcnt(6)
	v_mfma_f32_32x32x16_bf16 v[98:113], v[206:209], v[180:183], v[98:113]
	ds_read_b128 v[206:209], v235 offset:16384
	s_waitcnt lgkmcnt(6)
	v_mfma_f32_32x32x16_bf16 v[114:129], v[210:213], v[180:183], v[114:129]
	ds_read_b128 v[210:213], v235 offset:32768
	s_waitcnt lgkmcnt(6)
	v_mfma_f32_32x32x16_bf16 v[2:17], v[214:217], v[180:183], v[2:17]
	ds_read_b128 v[214:217], v235 offset:49152
	s_waitcnt lgkmcnt(6)
	v_mfma_f32_32x32x16_bf16 v[50:65], v[218:221], v[180:183], v[50:65]
	ds_read_b128 v[218:221], v236
	s_waitcnt lgkmcnt(6)
	v_mfma_f32_32x32x16_bf16 v[34:49], v[222:225], v[180:183], v[34:49]
	ds_read_b128 v[222:225], v236 offset:16384
	s_waitcnt lgkmcnt(6)
	v_mfma_f32_32x32x16_bf16 v[18:33], v[242:245], v[180:183], v[18:33]
	ds_read_b128 v[242:245], v236 offset:32768
	s_waitcnt lgkmcnt(6)
	v_mfma_f32_32x32x16_bf16 v[66:81], v[202:205], v[184:187], v[66:81]
	ds_read_b128 v[202:205], v236 offset:49152
	s_waitcnt lgkmcnt(6)
	v_mfma_f32_32x32x16_bf16 v[82:97], v[206:209], v[184:187], v[82:97]
	v_bitop3_b32 v237, v231, v234, 16 bitop3:0x36
	v_lshlrev_b32_e32 v237, 4, v237
	v_add3_u32 v235, 0, v237, v198
	v_add_u32_e32 v236, 0x10000, v235
	ds_read_b128 v[206:209], v235
	s_waitcnt lgkmcnt(6)
	v_mfma_f32_32x32x16_bf16 v[98:113], v[210:213], v[184:187], v[98:113]
	ds_read_b128 v[210:213], v235 offset:16384
	s_waitcnt lgkmcnt(6)
	v_mfma_f32_32x32x16_bf16 v[114:129], v[214:217], v[184:187], v[114:129]
	ds_read_b128 v[214:217], v235 offset:32768
	s_waitcnt lgkmcnt(6)
	v_mfma_f32_32x32x16_bf16 v[2:17], v[218:221], v[184:187], v[2:17]
	ds_read_b128 v[218:221], v235 offset:49152
	s_waitcnt lgkmcnt(6)
	v_mfma_f32_32x32x16_bf16 v[50:65], v[222:225], v[184:187], v[50:65]
	ds_read_b128 v[222:225], v236
	s_waitcnt lgkmcnt(6)
	v_mfma_f32_32x32x16_bf16 v[34:49], v[242:245], v[184:187], v[34:49]
	ds_read_b128 v[242:245], v236 offset:16384
	s_waitcnt lgkmcnt(6)
	v_mfma_f32_32x32x16_bf16 v[18:33], v[202:205], v[184:187], v[18:33]
	ds_read_b128 v[202:205], v236 offset:32768
	s_waitcnt lgkmcnt(6)
	v_mfma_f32_32x32x16_bf16 v[66:81], v[206:209], v[188:191], v[66:81]
	ds_read_b128 v[206:209], v236 offset:49152
	s_waitcnt lgkmcnt(6)
	v_mfma_f32_32x32x16_bf16 v[82:97], v[210:213], v[188:191], v[82:97]
	v_bitop3_b32 v237, v231, v234, 18 bitop3:0x36
	v_lshlrev_b32_e32 v237, 4, v237
	v_add3_u32 v235, 0, v237, v198
	v_add_u32_e32 v236, 0x10000, v235
	ds_read_b128 v[210:213], v235
	s_waitcnt lgkmcnt(6)
	v_mfma_f32_32x32x16_bf16 v[98:113], v[214:217], v[188:191], v[98:113]
	ds_read_b128 v[214:217], v235 offset:16384
	s_waitcnt lgkmcnt(6)
	v_mfma_f32_32x32x16_bf16 v[114:129], v[218:221], v[188:191], v[114:129]
	ds_read_b128 v[218:221], v235 offset:32768
	s_waitcnt lgkmcnt(6)
	v_mfma_f32_32x32x16_bf16 v[2:17], v[222:225], v[188:191], v[2:17]
	ds_read_b128 v[222:225], v235 offset:49152
	s_waitcnt lgkmcnt(6)
	v_mfma_f32_32x32x16_bf16 v[50:65], v[242:245], v[188:191], v[50:65]
	ds_read_b128 v[242:245], v236
	s_waitcnt lgkmcnt(6)
	v_mfma_f32_32x32x16_bf16 v[34:49], v[202:205], v[188:191], v[34:49]
	ds_read_b128 v[202:205], v236 offset:16384
	s_waitcnt lgkmcnt(6)
	v_mfma_f32_32x32x16_bf16 v[18:33], v[206:209], v[188:191], v[18:33]
	ds_read_b128 v[206:209], v236 offset:32768
	s_waitcnt lgkmcnt(6)
	v_mfma_f32_32x32x16_bf16 v[66:81], v[210:213], v[192:195], v[66:81]
	ds_read_b128 v[210:213], v236 offset:49152
	s_waitcnt lgkmcnt(6)
	v_mfma_f32_32x32x16_bf16 v[82:97], v[214:217], v[192:195], v[82:97]
	v_bitop3_b32 v237, v231, v234, 20 bitop3:0x36
	v_lshlrev_b32_e32 v237, 4, v237
	v_add3_u32 v235, 0, v237, v198
	v_add_u32_e32 v236, 0x10000, v235
	ds_read_b128 v[214:217], v235
	s_waitcnt lgkmcnt(6)
	v_mfma_f32_32x32x16_bf16 v[98:113], v[218:221], v[192:195], v[98:113]
	ds_read_b128 v[218:221], v235 offset:16384
	s_waitcnt lgkmcnt(6)
	v_mfma_f32_32x32x16_bf16 v[114:129], v[222:225], v[192:195], v[114:129]
	ds_read_b128 v[222:225], v235 offset:32768
	s_waitcnt lgkmcnt(6)
	v_mfma_f32_32x32x16_bf16 v[2:17], v[242:245], v[192:195], v[2:17]
	ds_read_b128 v[242:245], v235 offset:49152
	s_waitcnt lgkmcnt(6)
	v_mfma_f32_32x32x16_bf16 v[50:65], v[202:205], v[192:195], v[50:65]
	ds_read_b128 v[202:205], v236
	s_waitcnt lgkmcnt(6)
	v_mfma_f32_32x32x16_bf16 v[34:49], v[206:209], v[192:195], v[34:49]
	ds_read_b128 v[206:209], v236 offset:16384
	s_waitcnt lgkmcnt(6)
	v_mfma_f32_32x32x16_bf16 v[18:33], v[210:213], v[192:195], v[18:33]
	ds_read_b128 v[210:213], v236 offset:32768
	s_waitcnt lgkmcnt(6)
	v_mfma_f32_32x32x16_bf16 v[66:81], v[214:217], v[130:133], v[66:81]
	ds_read_b128 v[214:217], v236 offset:49152
	s_waitcnt lgkmcnt(6)
	v_mfma_f32_32x32x16_bf16 v[82:97], v[218:221], v[130:133], v[82:97]
	v_bitop3_b32 v237, v231, v234, 22 bitop3:0x36
	v_lshlrev_b32_e32 v237, 4, v237
	v_add3_u32 v235, 0, v237, v198
	v_add_u32_e32 v236, 0x10000, v235
	ds_read_b128 v[218:221], v235
	s_waitcnt lgkmcnt(6)
	v_mfma_f32_32x32x16_bf16 v[98:113], v[222:225], v[130:133], v[98:113]
	ds_read_b128 v[222:225], v235 offset:16384
	s_waitcnt lgkmcnt(6)
	v_mfma_f32_32x32x16_bf16 v[114:129], v[242:245], v[130:133], v[114:129]
	ds_read_b128 v[242:245], v235 offset:32768
	s_waitcnt lgkmcnt(6)
	v_mfma_f32_32x32x16_bf16 v[2:17], v[202:205], v[130:133], v[2:17]
	ds_read_b128 v[202:205], v235 offset:49152
	s_waitcnt lgkmcnt(6)
	v_mfma_f32_32x32x16_bf16 v[50:65], v[206:209], v[130:133], v[50:65]
	ds_read_b128 v[206:209], v236
	s_waitcnt lgkmcnt(6)
	v_mfma_f32_32x32x16_bf16 v[34:49], v[210:213], v[130:133], v[34:49]
	ds_read_b128 v[210:213], v236 offset:16384
	s_waitcnt lgkmcnt(6)
	v_mfma_f32_32x32x16_bf16 v[18:33], v[214:217], v[130:133], v[18:33]
	ds_read_b128 v[214:217], v236 offset:32768
	s_waitcnt lgkmcnt(6)
	v_mfma_f32_32x32x16_bf16 v[66:81], v[218:221], v[134:137], v[66:81]
	ds_read_b128 v[218:221], v236 offset:49152
	s_waitcnt lgkmcnt(6)
	v_mfma_f32_32x32x16_bf16 v[82:97], v[222:225], v[134:137], v[82:97]
	v_bitop3_b32 v237, v231, v234, 24 bitop3:0x36
	v_lshlrev_b32_e32 v237, 4, v237
	v_add3_u32 v235, 0, v237, v198
	v_add_u32_e32 v236, 0x10000, v235
	ds_read_b128 v[222:225], v235
	s_waitcnt lgkmcnt(6)
	v_mfma_f32_32x32x16_bf16 v[98:113], v[242:245], v[134:137], v[98:113]
	ds_read_b128 v[242:245], v235 offset:16384
	s_waitcnt lgkmcnt(6)
	v_mfma_f32_32x32x16_bf16 v[114:129], v[202:205], v[134:137], v[114:129]
	ds_read_b128 v[202:205], v235 offset:32768
	s_waitcnt lgkmcnt(6)
	v_mfma_f32_32x32x16_bf16 v[2:17], v[206:209], v[134:137], v[2:17]
	ds_read_b128 v[206:209], v235 offset:49152
	s_waitcnt lgkmcnt(6)
	v_mfma_f32_32x32x16_bf16 v[50:65], v[210:213], v[134:137], v[50:65]
	ds_read_b128 v[210:213], v236
	s_waitcnt lgkmcnt(6)
	v_mfma_f32_32x32x16_bf16 v[34:49], v[214:217], v[134:137], v[34:49]
	ds_read_b128 v[214:217], v236 offset:16384
	s_waitcnt lgkmcnt(6)
	v_mfma_f32_32x32x16_bf16 v[18:33], v[218:221], v[134:137], v[18:33]
	ds_read_b128 v[218:221], v236 offset:32768
	s_waitcnt lgkmcnt(6)
	v_mfma_f32_32x32x16_bf16 v[66:81], v[222:225], v[138:141], v[66:81]
	ds_read_b128 v[222:225], v236 offset:49152
	s_waitcnt lgkmcnt(6)
	v_mfma_f32_32x32x16_bf16 v[82:97], v[242:245], v[138:141], v[82:97]
	v_bitop3_b32 v237, v231, v234, 26 bitop3:0x36
	v_lshlrev_b32_e32 v237, 4, v237
	v_add3_u32 v235, 0, v237, v198
	v_add_u32_e32 v236, 0x10000, v235
	ds_read_b128 v[242:245], v235
	s_waitcnt lgkmcnt(6)
	v_mfma_f32_32x32x16_bf16 v[98:113], v[202:205], v[138:141], v[98:113]
	ds_read_b128 v[202:205], v235 offset:16384
	s_waitcnt lgkmcnt(6)
	v_mfma_f32_32x32x16_bf16 v[114:129], v[206:209], v[138:141], v[114:129]
	ds_read_b128 v[206:209], v235 offset:32768
	s_waitcnt lgkmcnt(6)
	v_mfma_f32_32x32x16_bf16 v[2:17], v[210:213], v[138:141], v[2:17]
	ds_read_b128 v[210:213], v235 offset:49152
	s_waitcnt lgkmcnt(6)
	v_mfma_f32_32x32x16_bf16 v[50:65], v[214:217], v[138:141], v[50:65]
	ds_read_b128 v[214:217], v236
	s_waitcnt lgkmcnt(6)
	v_mfma_f32_32x32x16_bf16 v[34:49], v[218:221], v[138:141], v[34:49]
	ds_read_b128 v[218:221], v236 offset:16384
	s_waitcnt lgkmcnt(6)
	v_mfma_f32_32x32x16_bf16 v[18:33], v[222:225], v[138:141], v[18:33]
	ds_read_b128 v[222:225], v236 offset:32768
	s_waitcnt lgkmcnt(6)
	v_mfma_f32_32x32x16_bf16 v[66:81], v[242:245], v[142:145], v[66:81]
	ds_read_b128 v[242:245], v236 offset:49152
	s_waitcnt lgkmcnt(6)
	v_mfma_f32_32x32x16_bf16 v[82:97], v[202:205], v[142:145], v[82:97]
	v_bitop3_b32 v237, v231, v234, 28 bitop3:0x36
	v_lshlrev_b32_e32 v237, 4, v237
	v_add3_u32 v235, 0, v237, v198
	v_add_u32_e32 v236, 0x10000, v235
	ds_read_b128 v[202:205], v235
	s_waitcnt lgkmcnt(6)
	v_mfma_f32_32x32x16_bf16 v[98:113], v[206:209], v[142:145], v[98:113]
	ds_read_b128 v[206:209], v235 offset:16384
	s_waitcnt lgkmcnt(6)
	v_mfma_f32_32x32x16_bf16 v[114:129], v[210:213], v[142:145], v[114:129]
	ds_read_b128 v[210:213], v235 offset:32768
	s_waitcnt lgkmcnt(6)
	v_mfma_f32_32x32x16_bf16 v[2:17], v[214:217], v[142:145], v[2:17]
	ds_read_b128 v[214:217], v235 offset:49152
	s_waitcnt lgkmcnt(6)
	v_mfma_f32_32x32x16_bf16 v[50:65], v[218:221], v[142:145], v[50:65]
	ds_read_b128 v[218:221], v236
	s_waitcnt lgkmcnt(6)
	v_mfma_f32_32x32x16_bf16 v[34:49], v[222:225], v[142:145], v[34:49]
	ds_read_b128 v[222:225], v236 offset:16384
	s_waitcnt lgkmcnt(6)
	v_mfma_f32_32x32x16_bf16 v[18:33], v[242:245], v[142:145], v[18:33]
	ds_read_b128 v[242:245], v236 offset:32768
	s_waitcnt lgkmcnt(6)
	v_mfma_f32_32x32x16_bf16 v[66:81], v[202:205], v[146:149], v[66:81]
	ds_read_b128 v[202:205], v236 offset:49152
	s_waitcnt lgkmcnt(6)
	v_mfma_f32_32x32x16_bf16 v[82:97], v[206:209], v[146:149], v[82:97]
	v_bitop3_b32 v237, v231, v234, 30 bitop3:0x36
	v_lshlrev_b32_e32 v237, 4, v237
	v_add3_u32 v235, 0, v237, v198
	v_add_u32_e32 v236, 0x10000, v235
	ds_read_b128 v[206:209], v235
	s_waitcnt lgkmcnt(6)
	v_mfma_f32_32x32x16_bf16 v[98:113], v[210:213], v[146:149], v[98:113]
	ds_read_b128 v[210:213], v235 offset:16384
	s_waitcnt lgkmcnt(6)
	v_mfma_f32_32x32x16_bf16 v[114:129], v[214:217], v[146:149], v[114:129]
	ds_read_b128 v[214:217], v235 offset:32768
	s_waitcnt lgkmcnt(6)
	v_mfma_f32_32x32x16_bf16 v[2:17], v[218:221], v[146:149], v[2:17]
	ds_read_b128 v[218:221], v235 offset:49152
	s_waitcnt lgkmcnt(6)
	v_mfma_f32_32x32x16_bf16 v[50:65], v[222:225], v[146:149], v[50:65]
	ds_read_b128 v[222:225], v236
	s_waitcnt lgkmcnt(6)
	v_mfma_f32_32x32x16_bf16 v[34:49], v[242:245], v[146:149], v[34:49]
	ds_read_b128 v[242:245], v236 offset:16384
	s_waitcnt lgkmcnt(6)
	v_mfma_f32_32x32x16_bf16 v[18:33], v[202:205], v[146:149], v[18:33]
	ds_read_b128 v[202:205], v236 offset:32768
	s_waitcnt lgkmcnt(6)
	v_mfma_f32_32x32x16_bf16 v[66:81], v[206:209], v[150:153], v[66:81]
	ds_read_b128 v[206:209], v236 offset:49152
	s_waitcnt lgkmcnt(6)
	v_mfma_f32_32x32x16_bf16 v[82:97], v[210:213], v[150:153], v[82:97]
	s_waitcnt lgkmcnt(5)
	v_mfma_f32_32x32x16_bf16 v[98:113], v[214:217], v[150:153], v[98:113]
	s_waitcnt lgkmcnt(4)
	v_mfma_f32_32x32x16_bf16 v[114:129], v[218:221], v[150:153], v[114:129]
	s_waitcnt lgkmcnt(3)
	v_mfma_f32_32x32x16_bf16 v[2:17], v[222:225], v[150:153], v[2:17]
	s_waitcnt lgkmcnt(2)
	v_mfma_f32_32x32x16_bf16 v[50:65], v[242:245], v[150:153], v[50:65]
	s_waitcnt lgkmcnt(1)
	v_mfma_f32_32x32x16_bf16 v[34:49], v[202:205], v[150:153], v[34:49]
	s_waitcnt lgkmcnt(0)
	v_mfma_f32_32x32x16_bf16 v[18:33], v[206:209], v[150:153], v[18:33]
	v_mov_b32_e32 v130, v254
	v_lshlrev_b32_e32 v0, 3, v231
	v_lshlrev_b32_e32 v131, 2, v231
	v_and_b32_e32 v140, 3, v230
	s_waitcnt lgkmcnt(0)
	s_waitcnt lgkmcnt(0)
	s_barrier
	v_mov_b64_e32 v[156:157], v[252:253]
	v_lshrrev_b32_e32 v235, 1, v230
	v_and_b32_e32 v235, 0xffffffe0, v235
	v_or_b32_e32 v235, v235, v231
	s_mov_b64 s[4:5], 0x2000
	v_add_u32_e32 v158, 2, v235
	v_lshl_add_u64 v[160:161], v[156:157], 0, s[4:5]
	v_add_u32_e32 v162, 4, v235
	v_lshl_add_u64 v[164:165], v[160:161], 0, s[4:5]
	v_add_u32_e32 v166, 6, v235
	v_lshl_add_u64 v[168:169], v[164:165], 0, s[4:5]
	v_add_u32_e32 v170, 8, v235
	v_lshl_add_u64 v[172:173], v[168:169], 0, s[4:5]
	v_add_u32_e32 v174, 10, v235
	v_lshl_add_u64 v[176:177], v[172:173], 0, s[4:5]
	v_add_u32_e32 v178, 12, v235
	v_lshl_add_u64 v[180:181], v[176:177], 0, s[4:5]
	v_add_u32_e32 v182, 14, v235
	v_lshl_add_u64 v[184:185], v[180:181], 0, s[4:5]
	v_add_u32_e32 v186, 16, v235
	v_lshl_add_u64 v[188:189], v[184:185], 0, s[4:5]
	v_add_u32_e32 v190, 18, v235
	v_lshl_add_u64 v[192:193], v[188:189], 0, s[4:5]
	v_add_u32_e32 v202, 20, v235
	v_lshl_add_u64 v[204:205], v[192:193], 0, s[4:5]
	v_add_u32_e32 v206, 22, v235
	v_lshl_add_u64 v[208:209], v[204:205], 0, s[4:5]
	v_add_u32_e32 v210, 24, v235
	v_lshl_add_u64 v[212:213], v[208:209], 0, s[4:5]
	v_add_u32_e32 v214, 26, v235
	v_lshl_add_u64 v[216:217], v[212:213], 0, s[4:5]
	v_add_u32_e32 v218, 28, v235
	v_lshl_add_u64 v[220:221], v[216:217], 0, s[4:5]
	v_add_u32_e32 v222, 30, v235
	v_lshl_add_u64 v[224:225], v[220:221], 0, s[4:5]
	v_bitop3_b32 v132, v131, v230, 28 bitop3:0x78
	v_or_b32_e32 v132, v132, v140
	v_lshlrev_b32_e32 v132, 4, v132
	v_mov_b32_e32 v133, v1
	v_lshl_add_u64 v[132:133], v[156:157], 0, v[132:133]
	v_lshl_add_u64 v[132:133], v[132:133], 0, s[48:49]
	s_mov_b32 s4, m0
	s_mov_b32 m0, s24
	s_nop 0
	global_load_lds_dwordx4 v[132:133], off
	s_mov_b32 m0, s4
	v_lshlrev_b32_e32 v132, 2, v158
	v_xor_b32_e32 v132, v132, v230
	v_and_or_b32 v132, v132, 28, v140
	v_lshlrev_b32_e32 v132, 4, v132
	v_mov_b32_e32 v133, v1
	v_lshl_add_u64 v[132:133], v[160:161], 0, v[132:133]
	v_lshl_add_u64 v[132:133], v[132:133], 0, s[48:49]
	s_mov_b32 s4, m0
	s_mov_b32 m0, s25
	s_nop 0
	global_load_lds_dwordx4 v[132:133], off
	s_mov_b32 m0, s4
	v_lshlrev_b32_e32 v132, 2, v162
	v_xor_b32_e32 v132, v132, v230
	v_and_or_b32 v132, v132, 28, v140
	v_lshlrev_b32_e32 v132, 4, v132
	v_mov_b32_e32 v133, v1
	v_lshl_add_u64 v[132:133], v[164:165], 0, v[132:133]
	v_lshl_add_u64 v[132:133], v[132:133], 0, s[48:49]
	s_mov_b32 s4, m0
	s_mov_b32 m0, s26
	s_nop 0
	global_load_lds_dwordx4 v[132:133], off
	s_mov_b32 m0, s4
	v_lshlrev_b32_e32 v132, 2, v166
	v_xor_b32_e32 v132, v132, v230
	v_and_or_b32 v132, v132, 28, v140
	v_lshlrev_b32_e32 v132, 4, v132
	v_mov_b32_e32 v133, v1
	v_lshl_add_u64 v[132:133], v[168:169], 0, v[132:133]
	v_lshl_add_u64 v[132:133], v[132:133], 0, s[48:49]
	s_mov_b32 s4, m0
	s_mov_b32 m0, s27
	s_nop 0
	global_load_lds_dwordx4 v[132:133], off
	s_mov_b32 m0, s4
	v_lshlrev_b32_e32 v132, 2, v170
	v_xor_b32_e32 v132, v132, v230
	v_and_or_b32 v132, v132, 28, v140
	v_lshlrev_b32_e32 v132, 4, v132
	v_mov_b32_e32 v133, v1
	v_lshl_add_u64 v[132:133], v[172:173], 0, v[132:133]
	v_lshl_add_u64 v[132:133], v[132:133], 0, s[48:49]
	s_mov_b32 s4, m0
	s_mov_b32 m0, s28
	s_nop 0
	global_load_lds_dwordx4 v[132:133], off
	s_mov_b32 m0, s4
	v_lshlrev_b32_e32 v132, 2, v174
	v_xor_b32_e32 v132, v132, v230
	v_and_or_b32 v132, v132, 28, v140
	v_lshlrev_b32_e32 v132, 4, v132
	v_mov_b32_e32 v133, v1
	v_lshl_add_u64 v[132:133], v[176:177], 0, v[132:133]
	v_lshl_add_u64 v[132:133], v[132:133], 0, s[48:49]
	s_mov_b32 s4, m0
	s_mov_b32 m0, s29
	s_nop 0
	global_load_lds_dwordx4 v[132:133], off
	s_mov_b32 m0, s4
	v_lshlrev_b32_e32 v132, 2, v178
	v_xor_b32_e32 v132, v132, v230
	v_and_or_b32 v132, v132, 28, v140
	v_lshlrev_b32_e32 v132, 4, v132
	v_mov_b32_e32 v133, v1
	v_lshl_add_u64 v[132:133], v[180:181], 0, v[132:133]
	v_lshl_add_u64 v[132:133], v[132:133], 0, s[48:49]
	s_mov_b32 s4, m0
	s_mov_b32 m0, s30
	s_nop 0
	global_load_lds_dwordx4 v[132:133], off
	s_mov_b32 m0, s4
	v_lshlrev_b32_e32 v132, 2, v182
	v_xor_b32_e32 v132, v132, v230
	v_and_or_b32 v132, v132, 28, v140
	v_lshlrev_b32_e32 v132, 4, v132
	v_mov_b32_e32 v133, v1
	v_lshl_add_u64 v[132:133], v[184:185], 0, v[132:133]
	v_lshl_add_u64 v[132:133], v[132:133], 0, s[48:49]
	s_mov_b32 s4, m0
	s_mov_b32 m0, s31
	s_nop 0
	global_load_lds_dwordx4 v[132:133], off
	s_mov_b32 m0, s4
	v_lshlrev_b32_e32 v132, 2, v186
	v_xor_b32_e32 v132, v132, v230
	v_and_or_b32 v132, v132, 28, v140
	v_lshlrev_b32_e32 v132, 4, v132
	v_mov_b32_e32 v133, v1
	v_lshl_add_u64 v[132:133], v[188:189], 0, v[132:133]
	v_lshl_add_u64 v[132:133], v[132:133], 0, s[48:49]
	s_mov_b32 s4, m0
	s_mov_b32 m0, s34
	s_nop 0
	global_load_lds_dwordx4 v[132:133], off
	s_mov_b32 m0, s4
	v_lshlrev_b32_e32 v132, 2, v190
	v_xor_b32_e32 v132, v132, v230
	v_and_or_b32 v132, v132, 28, v140
	v_lshlrev_b32_e32 v132, 4, v132
	v_mov_b32_e32 v133, v1
	v_lshl_add_u64 v[132:133], v[192:193], 0, v[132:133]
	v_lshl_add_u64 v[132:133], v[132:133], 0, s[48:49]
	s_mov_b32 s4, m0
	s_mov_b32 m0, s35
	s_nop 0
	global_load_lds_dwordx4 v[132:133], off
	s_mov_b32 m0, s4
	v_lshlrev_b32_e32 v132, 2, v202
	v_xor_b32_e32 v132, v132, v230
	v_and_or_b32 v132, v132, 28, v140
	v_lshlrev_b32_e32 v132, 4, v132
	v_mov_b32_e32 v133, v1
	v_lshl_add_u64 v[132:133], v[204:205], 0, v[132:133]
	v_lshl_add_u64 v[132:133], v[132:133], 0, s[48:49]
	s_mov_b32 s4, m0
	s_mov_b32 m0, s36
	s_nop 0
	global_load_lds_dwordx4 v[132:133], off
	s_mov_b32 m0, s4
	v_lshlrev_b32_e32 v132, 2, v206
	v_xor_b32_e32 v132, v132, v230
	v_and_or_b32 v132, v132, 28, v140
	v_lshlrev_b32_e32 v132, 4, v132
	v_mov_b32_e32 v133, v1
	v_lshl_add_u64 v[132:133], v[208:209], 0, v[132:133]
	v_lshl_add_u64 v[132:133], v[132:133], 0, s[48:49]
	s_mov_b32 s4, m0
	s_mov_b32 m0, s37
	s_nop 0
	global_load_lds_dwordx4 v[132:133], off
	s_mov_b32 m0, s4
	v_lshlrev_b32_e32 v132, 2, v210
	v_xor_b32_e32 v132, v132, v230
	v_and_or_b32 v132, v132, 28, v140
	v_lshlrev_b32_e32 v132, 4, v132
	v_mov_b32_e32 v133, v1
	v_lshl_add_u64 v[132:133], v[212:213], 0, v[132:133]
	v_lshl_add_u64 v[132:133], v[132:133], 0, s[48:49]
	s_mov_b32 s4, m0
	s_mov_b32 m0, s38
	s_nop 0
	global_load_lds_dwordx4 v[132:133], off
	s_mov_b32 m0, s4
	v_lshlrev_b32_e32 v132, 2, v214
	v_xor_b32_e32 v132, v132, v230
	v_and_or_b32 v132, v132, 28, v140
	v_lshlrev_b32_e32 v132, 4, v132
	v_mov_b32_e32 v133, v1
	v_lshl_add_u64 v[132:133], v[216:217], 0, v[132:133]
	v_lshl_add_u64 v[132:133], v[132:133], 0, s[48:49]
	s_mov_b32 s4, m0
	s_mov_b32 m0, s39
	s_nop 0
	global_load_lds_dwordx4 v[132:133], off
	s_mov_b32 m0, s4
	v_lshlrev_b32_e32 v132, 2, v218
	v_xor_b32_e32 v132, v132, v230
	v_and_or_b32 v132, v132, 28, v140
	v_lshlrev_b32_e32 v132, 4, v132
	v_mov_b32_e32 v133, v1
	v_lshl_add_u64 v[132:133], v[220:221], 0, v[132:133]
	v_lshl_add_u64 v[132:133], v[132:133], 0, s[48:49]
	s_mov_b32 s4, m0
	s_mov_b32 m0, s40
	s_nop 0
	global_load_lds_dwordx4 v[132:133], off
	s_mov_b32 m0, s4
	v_lshlrev_b32_e32 v132, 2, v222
	v_xor_b32_e32 v132, v132, v230
	v_and_or_b32 v132, v132, 28, v140
	v_lshlrev_b32_e32 v132, 4, v132
	v_mov_b32_e32 v133, v1
	v_lshl_add_u64 v[132:133], v[224:225], 0, v[132:133]
	v_lshl_add_u64 v[132:133], v[132:133], 0, s[48:49]
	s_mov_b32 s4, m0
	s_mov_b32 m0, s20
	s_nop 0
	global_load_lds_dwordx4 v[132:133], off
	s_mov_b32 m0, s4
	v_mul_f32_e32 v82, v130, v82
	v_exp_f32_e32 v133, v82
	v_mul_f32_e32 v82, v130, v83
	v_exp_f32_e32 v134, v82
	v_mul_f32_e32 v82, v130, v84
	v_exp_f32_e32 v135, v82
	v_mul_f32_e32 v82, v130, v85
	v_exp_f32_e32 v136, v82
	v_mul_f32_e32 v82, v130, v86
	v_exp_f32_e32 v137, v82
	v_mul_f32_e32 v82, v130, v87
	v_exp_f32_e32 v138, v82
	v_mul_f32_e32 v82, v130, v88
	v_exp_f32_e32 v139, v82
	v_mul_f32_e32 v82, v130, v89
	v_exp_f32_e32 v89, v82
	v_mul_f32_e32 v82, v130, v90
	v_exp_f32_e32 v140, v82
	v_mul_f32_e32 v82, v130, v91
	v_exp_f32_e32 v141, v82
	v_mul_f32_e32 v82, v130, v92
	v_exp_f32_e32 v142, v82
	v_mul_f32_e32 v82, v130, v93
	v_exp_f32_e32 v143, v82
	v_mul_f32_e32 v82, v130, v94
	v_exp_f32_e32 v144, v82
	v_mul_f32_e32 v82, v130, v95
	v_mul_f32_e32 v81, v130, v81
	v_mul_f32_e32 v66, v130, v66
	v_exp_f32_e32 v145, v82
	v_mul_f32_e32 v82, v130, v96
	v_exp_f32_e32 v147, v81
	v_exp_f32_e32 v81, v66
	v_mul_f32_e32 v66, v130, v67
	v_exp_f32_e32 v146, v82
	v_exp_f32_e32 v82, v66
	v_mul_f32_e32 v66, v130, v68
	v_exp_f32_e32 v83, v66
	v_mul_f32_e32 v66, v130, v69
	v_exp_f32_e32 v84, v66
	v_mul_f32_e32 v66, v130, v70
	v_exp_f32_e32 v85, v66
	v_mul_f32_e32 v66, v130, v71
	v_add_f32_e32 v90, 0, v81
	v_exp_f32_e32 v86, v66
	v_mul_f32_e32 v66, v130, v72
	v_add_f32_e32 v90, v82, v90
	v_exp_f32_e32 v87, v66
	v_mul_f32_e32 v66, v130, v73
	v_add_f32_e32 v90, v83, v90
	v_exp_f32_e32 v88, v66
	v_mul_f32_e32 v66, v130, v74
	v_add_f32_e32 v90, v84, v90
	v_exp_f32_e32 v74, v66
	v_mul_f32_e32 v66, v130, v75
	v_add_f32_e32 v90, v85, v90
	v_exp_f32_e32 v75, v66
	v_mul_f32_e32 v66, v130, v76
	v_add_f32_e32 v90, v86, v90
	v_exp_f32_e32 v76, v66
	v_mul_f32_e32 v66, v130, v77
	v_add_f32_e32 v90, v87, v90
	v_exp_f32_e32 v77, v66
	v_mul_f32_e32 v66, v130, v78
	v_add_f32_e32 v90, v88, v90
	v_exp_f32_e32 v78, v66
	v_mul_f32_e32 v66, v130, v79
	v_add_f32_e32 v90, v74, v90
	v_exp_f32_e32 v79, v66
	v_mul_f32_e32 v66, v130, v80
	v_add_f32_e32 v90, v75, v90
	v_exp_f32_e32 v80, v66
	v_add_f32_e32 v90, v76, v90
	v_add_f32_e32 v90, v77, v90
	v_add_f32_e32 v90, v78, v90
	v_add_f32_e32 v90, v79, v90
	v_add_f32_e32 v90, v80, v90
	v_add_f32_e32 v90, v147, v90
	v_add_f32_e32 v90, v133, v90
	v_add_f32_e32 v90, v134, v90
	v_add_f32_e32 v90, v135, v90
	v_add_f32_e32 v90, v136, v90
	v_add_f32_e32 v90, v137, v90
	v_add_f32_e32 v90, v138, v90
	v_add_f32_e32 v90, v139, v90
	v_add_f32_e32 v90, v89, v90
	v_add_f32_e32 v90, v140, v90
	v_add_f32_e32 v90, v141, v90
	v_mul_f32_e32 v97, v130, v97
	v_add_f32_e32 v90, v142, v90
	v_mul_f32_e32 v98, v130, v98
	v_exp_f32_e32 v132, v97
	v_add_f32_e32 v90, v143, v90
	v_exp_f32_e32 v98, v98
	v_mul_f32_e32 v99, v130, v99
	v_add_f32_e32 v90, v144, v90
	v_exp_f32_e32 v99, v99
	v_mul_f32_e32 v100, v130, v100
	v_add_f32_e32 v90, v145, v90
	v_exp_f32_e32 v100, v100
	v_mul_f32_e32 v101, v130, v101
	v_add_f32_e32 v90, v146, v90
	v_exp_f32_e32 v101, v101
	v_mul_f32_e32 v102, v130, v102
	v_add_f32_e32 v90, v132, v90
	v_exp_f32_e32 v102, v102
	v_mul_f32_e32 v103, v130, v103
	v_add_f32_e32 v90, v98, v90
	v_exp_f32_e32 v103, v103
	v_mul_f32_e32 v104, v130, v104
	v_add_f32_e32 v90, v99, v90
	v_exp_f32_e32 v104, v104
	v_mul_f32_e32 v105, v130, v105
	v_add_f32_e32 v90, v100, v90
	v_exp_f32_e32 v105, v105
	v_mul_f32_e32 v106, v130, v106
	v_add_f32_e32 v90, v101, v90
	v_exp_f32_e32 v106, v106
	v_mul_f32_e32 v107, v130, v107
	v_add_f32_e32 v90, v102, v90
	v_exp_f32_e32 v107, v107
	v_mul_f32_e32 v108, v130, v108
	v_add_f32_e32 v90, v103, v90
	v_exp_f32_e32 v108, v108
	v_mul_f32_e32 v109, v130, v109
	v_add_f32_e32 v90, v104, v90
	v_exp_f32_e32 v109, v109
	v_mul_f32_e32 v110, v130, v110
	v_add_f32_e32 v90, v105, v90
	v_exp_f32_e32 v110, v110
	v_mul_f32_e32 v111, v130, v111
	v_add_f32_e32 v90, v106, v90
	v_exp_f32_e32 v111, v111
	v_mul_f32_e32 v112, v130, v112
	v_add_f32_e32 v90, v107, v90
	v_mul_f32_e32 v113, v130, v113
	v_exp_f32_e32 v112, v112
	v_add_f32_e32 v90, v108, v90
	v_mul_f32_e32 v114, v130, v114
	v_exp_f32_e32 v113, v113
	v_add_f32_e32 v90, v109, v90
	v_exp_f32_e32 v114, v114
	v_mul_f32_e32 v115, v130, v115
	v_add_f32_e32 v90, v110, v90
	v_exp_f32_e32 v115, v115
	v_mul_f32_e32 v116, v130, v116
	v_add_f32_e32 v90, v111, v90
	v_exp_f32_e32 v116, v116
	v_mul_f32_e32 v117, v130, v117
	v_add_f32_e32 v90, v112, v90
	v_exp_f32_e32 v117, v117
	v_mul_f32_e32 v118, v130, v118
	v_add_f32_e32 v90, v113, v90
	v_exp_f32_e32 v118, v118
	v_mul_f32_e32 v119, v130, v119
	v_add_f32_e32 v90, v114, v90
	v_exp_f32_e32 v119, v119
	v_mul_f32_e32 v120, v130, v120
	v_add_f32_e32 v90, v115, v90
	v_exp_f32_e32 v120, v120
	v_mul_f32_e32 v121, v130, v121
	v_add_f32_e32 v90, v116, v90
	v_exp_f32_e32 v121, v121
	v_mul_f32_e32 v122, v130, v122
	v_add_f32_e32 v90, v117, v90
	v_exp_f32_e32 v122, v122
	v_mul_f32_e32 v123, v130, v123
	v_add_f32_e32 v90, v118, v90
	v_exp_f32_e32 v123, v123
	v_mul_f32_e32 v124, v130, v124
	v_add_f32_e32 v90, v119, v90
	v_exp_f32_e32 v124, v124
	v_mul_f32_e32 v125, v130, v125
	v_add_f32_e32 v90, v120, v90
	v_exp_f32_e32 v125, v125
	v_mul_f32_e32 v126, v130, v126
	v_add_f32_e32 v90, v121, v90
	v_exp_f32_e32 v126, v126
	v_mul_f32_e32 v127, v130, v127
	v_add_f32_e32 v90, v122, v90
	v_exp_f32_e32 v127, v127
	v_mul_f32_e32 v128, v130, v128
	v_add_f32_e32 v90, v123, v90
	v_mul_f32_e32 v129, v130, v129
	v_exp_f32_e32 v128, v128
	v_add_f32_e32 v90, v124, v90
	v_exp_f32_e32 v129, v129
	v_add_f32_e32 v90, v125, v90
	v_mul_f32_e32 v2, v130, v2
	v_add_f32_e32 v90, v126, v90
	v_exp_f32_e32 v2, v2
	v_mul_f32_e32 v3, v130, v3
	v_add_f32_e32 v90, v127, v90
	v_exp_f32_e32 v3, v3
	v_mul_f32_e32 v4, v130, v4
	v_add_f32_e32 v90, v128, v90
	v_exp_f32_e32 v4, v4
	v_mul_f32_e32 v5, v130, v5
	v_add_f32_e32 v148, v129, v90
	v_exp_f32_e32 v5, v5
	v_mul_f32_e32 v6, v130, v6
	v_cvt_pk_bf16_f32 v66, v122, v123
	v_cvt_pk_bf16_f32 v122, v74, v75
	v_add_f32_e32 v74, v148, v2
	v_exp_f32_e32 v6, v6
	v_mul_f32_e32 v7, v130, v7
	v_add_f32_e32 v74, v3, v74
	v_exp_f32_e32 v7, v7
	v_mul_f32_e32 v8, v130, v8
	v_add_f32_e32 v74, v4, v74
	v_exp_f32_e32 v8, v8
	v_mul_f32_e32 v9, v130, v9
	v_add_f32_e32 v74, v5, v74
	v_exp_f32_e32 v9, v9
	v_mul_f32_e32 v10, v130, v10
	v_add_f32_e32 v74, v6, v74
	v_exp_f32_e32 v10, v10
	v_mul_f32_e32 v11, v130, v11
	v_add_f32_e32 v74, v7, v74
	v_exp_f32_e32 v11, v11
	v_mul_f32_e32 v12, v130, v12
	v_add_f32_e32 v74, v8, v74
	v_exp_f32_e32 v12, v12
	v_mul_f32_e32 v13, v130, v13
	v_add_f32_e32 v74, v9, v74
	v_exp_f32_e32 v13, v13
	v_mul_f32_e32 v14, v130, v14
	v_add_f32_e32 v74, v10, v74
	v_exp_f32_e32 v14, v14
	v_mul_f32_e32 v15, v130, v15
	v_add_f32_e32 v74, v11, v74
	v_exp_f32_e32 v15, v15
	v_mul_f32_e32 v16, v130, v16
	v_add_f32_e32 v74, v12, v74
	v_exp_f32_e32 v16, v16
	v_mul_f32_e32 v17, v130, v17
	v_cvt_pk_bf16_f32 v92, v110, v111
	v_add_f32_e32 v74, v13, v74
	v_exp_f32_e32 v17, v17
	v_cvt_pk_bf16_f32 v110, v2, v3
	v_mul_f32_e32 v2, v130, v50
	v_add_f32_e32 v74, v14, v74
	v_cvt_pk_bf16_f32 v111, v4, v5
	v_exp_f32_e32 v2, v2
	v_mul_f32_e32 v4, v130, v51
	v_add_f32_e32 v74, v15, v74
	v_exp_f32_e32 v4, v4
	v_mul_f32_e32 v5, v130, v52
	v_cvt_pk_bf16_f32 v93, v112, v113
	v_add_f32_e32 v74, v16, v74
	v_cvt_pk_bf16_f32 v112, v6, v7
	v_exp_f32_e32 v5, v5
	v_mul_f32_e32 v6, v130, v53
	v_add_f32_e32 v74, v17, v74
	v_exp_f32_e32 v6, v6
	v_mul_f32_e32 v7, v130, v54
	v_cvt_pk_bf16_f32 v113, v8, v9
	v_add_f32_e32 v3, v2, v74
	v_exp_f32_e32 v7, v7
	v_mul_f32_e32 v8, v130, v55
	v_add_f32_e32 v3, v4, v3
	v_exp_f32_e32 v8, v8
	v_mul_f32_e32 v9, v130, v56
	v_cvt_pk_bf16_f32 v90, v106, v107
	v_cvt_pk_bf16_f32 v106, v10, v11
	v_add_f32_e32 v3, v5, v3
	v_exp_f32_e32 v9, v9
	v_mul_f32_e32 v10, v130, v57
	v_add_f32_e32 v3, v6, v3
	v_exp_f32_e32 v10, v10
	v_mul_f32_e32 v11, v130, v58
	v_cvt_pk_bf16_f32 v107, v12, v13
	v_add_f32_e32 v3, v7, v3
	v_exp_f32_e32 v11, v11
	v_mul_f32_e32 v12, v130, v59
	v_add_f32_e32 v3, v8, v3
	v_exp_f32_e32 v12, v12
	v_mul_f32_e32 v13, v130, v60
	v_cvt_pk_bf16_f32 v91, v108, v109
	v_cvt_pk_bf16_f32 v108, v14, v15
	v_add_f32_e32 v3, v9, v3
	v_exp_f32_e32 v13, v13
	v_mul_f32_e32 v14, v130, v61
	v_add_f32_e32 v3, v10, v3
	v_exp_f32_e32 v14, v14
	v_mul_f32_e32 v15, v130, v62
	v_cvt_pk_bf16_f32 v109, v16, v17
	v_add_f32_e32 v3, v11, v3
	v_exp_f32_e32 v15, v15
	v_mul_f32_e32 v16, v130, v63
	v_add_f32_e32 v3, v12, v3
	v_exp_f32_e32 v16, v16
	v_mul_f32_e32 v17, v130, v64
	v_add_f32_e32 v3, v13, v3
	v_exp_f32_e32 v17, v17
	v_mul_f32_e32 v50, v130, v65
	v_cvt_pk_bf16_f32 v96, v102, v103
	v_add_f32_e32 v3, v14, v3
	v_exp_f32_e32 v50, v50
	v_cvt_pk_bf16_f32 v102, v2, v4
	v_mul_f32_e32 v2, v130, v34
	v_add_f32_e32 v3, v15, v3
	v_exp_f32_e32 v2, v2
	v_mul_f32_e32 v4, v130, v35
	v_add_f32_e32 v3, v16, v3
	v_cvt_pk_bf16_f32 v103, v5, v6
	v_exp_f32_e32 v4, v4
	v_mul_f32_e32 v5, v130, v36
	v_add_f32_e32 v3, v17, v3
	v_exp_f32_e32 v5, v5
	v_mul_f32_e32 v6, v130, v37
	v_cvt_pk_bf16_f32 v97, v104, v105
	v_add_f32_e32 v3, v50, v3
	v_cvt_pk_bf16_f32 v104, v7, v8
	v_exp_f32_e32 v6, v6
	v_mul_f32_e32 v7, v130, v38
	v_add_f32_e32 v3, v2, v3
	v_exp_f32_e32 v7, v7
	v_mul_f32_e32 v8, v130, v39
	v_cvt_pk_bf16_f32 v105, v9, v10
	v_add_f32_e32 v3, v4, v3
	v_exp_f32_e32 v8, v8
	v_mul_f32_e32 v9, v130, v40
	v_add_f32_e32 v3, v5, v3
	v_exp_f32_e32 v9, v9
	v_mul_f32_e32 v10, v130, v41
	v_cvt_pk_bf16_f32 v94, v98, v99
	v_cvt_pk_bf16_f32 v98, v11, v12
	v_add_f32_e32 v3, v6, v3
	v_exp_f32_e32 v10, v10
	v_mul_f32_e32 v11, v130, v42
	v_add_f32_e32 v3, v7, v3
	v_exp_f32_e32 v11, v11
	v_mul_f32_e32 v12, v130, v43
	v_cvt_pk_bf16_f32 v99, v13, v14
	v_add_f32_e32 v3, v8, v3
	v_exp_f32_e32 v12, v12
	v_mul_f32_e32 v13, v130, v44
	v_add_f32_e32 v3, v9, v3
	v_exp_f32_e32 v13, v13
	v_mul_f32_e32 v14, v130, v45
	v_cvt_pk_bf16_f32 v95, v100, v101
	v_cvt_pk_bf16_f32 v100, v15, v16
	v_add_f32_e32 v3, v10, v3
	v_exp_f32_e32 v14, v14
	v_mul_f32_e32 v15, v130, v46
	v_add_f32_e32 v3, v11, v3
	v_exp_f32_e32 v15, v15
	v_mul_f32_e32 v16, v130, v47
	v_cvt_pk_bf16_f32 v101, v17, v50
	v_add_f32_e32 v3, v12, v3
	v_exp_f32_e32 v16, v16
	v_mul_f32_e32 v17, v130, v48
	v_add_f32_e32 v3, v13, v3
	v_exp_f32_e32 v17, v17
	v_mul_f32_e32 v34, v130, v49
	v_cvt_pk_bf16_f32 v69, v128, v129
	v_cvt_pk_bf16_f32 v128, v85, v86
	v_add_f32_e32 v3, v14, v3
	v_exp_f32_e32 v34, v34
	v_cvt_pk_bf16_f32 v86, v2, v4
	v_mul_f32_e32 v2, v130, v18
	v_add_f32_e32 v3, v15, v3
	v_exp_f32_e32 v2, v2
	v_mul_f32_e32 v4, v130, v19
	v_cvt_pk_bf16_f32 v129, v87, v88
	v_add_f32_e32 v3, v16, v3
	v_cvt_pk_bf16_f32 v87, v5, v6
	v_exp_f32_e32 v4, v4
	v_mul_f32_e32 v5, v130, v20
	v_add_f32_e32 v3, v17, v3
	v_exp_f32_e32 v5, v5
	v_mul_f32_e32 v6, v130, v21
	v_add_f32_e32 v3, v34, v3
	v_cvt_pk_bf16_f32 v88, v7, v8
	v_exp_f32_e32 v6, v6
	v_mul_f32_e32 v7, v130, v22
	v_add_f32_e32 v3, v2, v3
	v_exp_f32_e32 v7, v7
	v_mul_f32_e32 v8, v130, v23
	v_cvt_pk_bf16_f32 v73, v120, v121
	v_cvt_pk_bf16_f32 v121, v139, v89
	v_cvt_pk_bf16_f32 v89, v9, v10
	v_add_f32_e32 v3, v4, v3
	v_exp_f32_e32 v8, v8
	v_mul_f32_e32 v9, v130, v24
	v_add_f32_e32 v3, v5, v3
	v_exp_f32_e32 v9, v9
	v_mul_f32_e32 v10, v130, v25
	v_cvt_pk_bf16_f32 v68, v126, v127
	v_cvt_pk_bf16_f32 v126, v81, v82
	v_cvt_pk_bf16_f32 v82, v11, v12
	v_add_f32_e32 v3, v6, v3
	v_exp_f32_e32 v10, v10
	v_mul_f32_e32 v11, v130, v26
	v_add_f32_e32 v3, v7, v3
	v_exp_f32_e32 v11, v11
	v_mul_f32_e32 v12, v130, v27
	v_cvt_pk_bf16_f32 v127, v83, v84
	v_cvt_pk_bf16_f32 v83, v13, v14
	v_add_f32_e32 v3, v8, v3
	v_exp_f32_e32 v12, v12
	v_mul_f32_e32 v13, v130, v28
	v_add_f32_e32 v3, v9, v3
	v_exp_f32_e32 v13, v13
	v_mul_f32_e32 v14, v130, v29
	v_cvt_pk_bf16_f32 v84, v15, v16
	v_add_f32_e32 v3, v10, v3
	v_exp_f32_e32 v14, v14
	v_mul_f32_e32 v15, v130, v30
	v_add_f32_e32 v3, v11, v3
	v_exp_f32_e32 v15, v15
	v_mul_f32_e32 v16, v130, v31
	v_cvt_pk_bf16_f32 v85, v17, v34
	v_add_f32_e32 v3, v12, v3
	v_exp_f32_e32 v16, v16
	v_mul_f32_e32 v17, v130, v32
	v_add_f32_e32 v3, v13, v3
	v_exp_f32_e32 v17, v17
	v_mul_f32_e32 v18, v130, v33
	v_cvt_pk_bf16_f32 v67, v124, v125
	v_cvt_pk_bf16_f32 v124, v78, v79
	v_add_f32_e32 v3, v14, v3
	v_exp_f32_e32 v18, v18
	v_cvt_pk_bf16_f32 v78, v2, v4
	v_and_b32_e32 v4, 64, v238
	v_add_f32_e32 v3, v15, v3
	v_xor_b32_e32 v2, 32, v238
	v_add_u32_e32 v4, 64, v4
	v_add_f32_e32 v3, v16, v3
	v_cmp_lt_i32_e32 vcc, v2, v4
	v_add_f32_e32 v3, v17, v3
	v_add_f32_e32 v3, v18, v3
	v_cndmask_b32_e32 v2, v238, v2, vcc
	v_lshlrev_b32_e32 v2, 2, v2
	ds_bpermute_b32 v2, v2, v3
	v_cvt_pk_bf16_f32 v79, v5, v6
	v_cvt_pk_bf16_f32 v125, v80, v147
	v_cvt_pk_bf16_f32 v80, v7, v8
	v_cvt_pk_bf16_f32 v71, v116, v117
	s_waitcnt lgkmcnt(0)
	v_add_f32_e32 v2, v3, v2
	v_div_scale_f32 v3, s[18:19], v2, v2, 1.0
	v_rcp_f32_e32 v4, v3
	v_cvt_pk_bf16_f32 v72, v118, v119
	v_cvt_pk_bf16_f32 v117, v146, v132
	v_cvt_pk_bf16_f32 v118, v133, v134
	v_fma_f32 v5, -v3, v4, 1.0
	v_fmac_f32_e32 v4, v5, v4
	v_div_scale_f32 v5, vcc, 1.0, v2, 1.0
	v_mul_f32_e32 v6, v5, v4
	v_fma_f32 v7, -v3, v6, v5
	v_fmac_f32_e32 v6, v7, v4
	v_fma_f32 v3, -v3, v6, v5
	v_div_fmas_f32 v3, v3, v4, v6
	v_div_fixup_f32 v130, v3, v2, 1.0
	v_lshl_add_u64 v[2:3], s[12:13], 0, v[154:155]
	v_lshl_add_u64 v[2:3], v[2:3], 0, s[16:17]
	v_lshrrev_b32_e32 v4, 2, v230
	v_lshl_add_u64 v[2:3], v[2:3], 0, v[0:1]
	v_lshlrev_b32_e32 v5, 1, v230
	v_lshlrev_b32_e32 v6, 3, v230
	v_lshl_add_u64 v[132:133], v[2:3], 0, v[0:1]
	v_and_or_b32 v0, v4, 3, v131
	v_and_b32_e32 v5, 32, v5
	v_and_b32_e32 v6, 24, v6
	v_lshl_add_u32 v2, v0, 9, 0
	v_add3_u32 v148, v2, v5, v6
	v_lshlrev_b32_e32 v149, 6, v0
	v_add_u32_e32 v0, v148, v149
	s_waitcnt vmcnt(0)
	s_barrier
	ds_read_b64_tr_b16 v[2:3], v0
	ds_read_b64_tr_b16 v[4:5], v0 offset:4096
	v_xor_b32_e32 v166, 64, v149
	v_add_u32_e32 v131, v148, v166
	v_cvt_pk_bf16_f32 v123, v76, v77
	v_cvt_pk_bf16_f32 v81, v9, v10
	v_cvt_pk_bf16_f32 v74, v11, v12
	v_cvt_pk_bf16_f32 v75, v13, v14
	v_cvt_pk_bf16_f32 v77, v17, v18
	ds_read_b64_tr_b16 v[6:7], v131
	ds_read_b64_tr_b16 v[8:9], v131 offset:4096
	ds_read_b64_tr_b16 v[10:11], v0 offset:8192
	ds_read_b64_tr_b16 v[12:13], v0 offset:12288
	ds_read_b64_tr_b16 v[18:19], v131 offset:8192
	ds_read_b64_tr_b16 v[20:21], v131 offset:12288
	s_waitcnt lgkmcnt(6)
	v_mfma_f32_32x32x16_bf16 v[34:49], v[2:5], v[126:129], 0
	v_cvt_pk_bf16_f32 v76, v15, v16
	v_cvt_pk_bf16_f32 v70, v114, v115
	v_cvt_pk_bf16_f32 v114, v140, v141
	v_cvt_pk_bf16_f32 v115, v142, v143
	v_cvt_pk_bf16_f32 v116, v144, v145
	v_cvt_pk_bf16_f32 v119, v135, v136
	v_cvt_pk_bf16_f32 v120, v137, v138
	s_waitcnt lgkmcnt(2)
	v_mfma_f32_32x32x16_bf16 v[50:65], v[10:13], v[122:125], 0
	ds_read_b64_tr_b16 v[134:135], v0 offset:16384
	ds_read_b64_tr_b16 v[136:137], v0 offset:20480
	ds_read_b64_tr_b16 v[138:139], v131 offset:16384
	ds_read_b64_tr_b16 v[140:141], v131 offset:20480
	ds_read_b64_tr_b16 v[142:143], v0 offset:24576
	ds_read_b64_tr_b16 v[144:145], v0 offset:28672
	ds_read_b64_tr_b16 v[150:151], v131 offset:24576
	ds_read_b64_tr_b16 v[152:153], v131 offset:28672
	v_add_u32_e32 v147, 0x10000, v148
	v_add_u32_e32 v146, 0x11000, v148
	v_xor_b32_e32 v168, 0xc0, v149
	v_add_u32_e32 v169, v148, v168
	s_add_u32 s14, s14, s46
	s_addc_u32 s15, s15, s47
	v_mfma_f32_32x32x16_bf16 v[2:17], v[6:9], v[126:129], 0
	s_mov_b64 s[16:17], 0
	s_waitcnt lgkmcnt(8)
	v_mfma_f32_32x32x16_bf16 v[18:33], v[18:21], v[122:125], 0
	s_waitcnt lgkmcnt(6)
	v_mfma_f32_32x32x16_bf16 v[34:49], v[134:137], v[118:121], v[34:49]
	s_waitcnt lgkmcnt(2)
	v_mfma_f32_32x32x16_bf16 v[50:65], v[142:145], v[114:117], v[50:65]
	v_mfma_f32_32x32x16_bf16 v[2:17], v[138:141], v[118:121], v[2:17]
	s_waitcnt lgkmcnt(0)
	v_mfma_f32_32x32x16_bf16 v[18:33], v[150:153], v[114:117], v[18:33]
	ds_read_b64_tr_b16 v[134:135], v0 offset:32768
	ds_read_b64_tr_b16 v[136:137], v0 offset:36864
	ds_read_b64_tr_b16 v[138:139], v131 offset:32768
	ds_read_b64_tr_b16 v[140:141], v131 offset:36864
	ds_read_b64_tr_b16 v[142:143], v0 offset:40960
	ds_read_b64_tr_b16 v[144:145], v0 offset:45056
	ds_read_b64_tr_b16 v[150:151], v131 offset:40960
	ds_read_b64_tr_b16 v[152:153], v131 offset:45056
	s_waitcnt lgkmcnt(6)
	v_mfma_f32_32x32x16_bf16 v[34:49], v[134:137], v[94:97], v[34:49]
	s_waitcnt lgkmcnt(2)
	v_mfma_f32_32x32x16_bf16 v[50:65], v[142:145], v[90:93], v[50:65]
	v_mfma_f32_32x32x16_bf16 v[2:17], v[138:141], v[94:97], v[2:17]
	s_waitcnt lgkmcnt(0)
	v_mfma_f32_32x32x16_bf16 v[18:33], v[150:153], v[90:93], v[18:33]
	ds_read_b64_tr_b16 v[134:135], v0 offset:49152
	ds_read_b64_tr_b16 v[136:137], v0 offset:53248
	ds_read_b64_tr_b16 v[138:139], v131 offset:49152
	ds_read_b64_tr_b16 v[140:141], v131 offset:53248
	ds_read_b64_tr_b16 v[142:143], v0 offset:57344
	ds_read_b64_tr_b16 v[144:145], v0 offset:61440
	ds_read_b64_tr_b16 v[150:151], v131 offset:57344
	ds_read_b64_tr_b16 v[152:153], v131 offset:61440
	v_add_u32_e32 v0, v147, v149
	v_add_u32_e32 v131, 0x1e000, v148
	s_waitcnt lgkmcnt(6)
	v_mfma_f32_32x32x16_bf16 v[34:49], v[134:137], v[70:73], v[34:49]
	ds_read_b64_tr_b16 v[134:135], v0
	v_add_u32_e32 v0, v146, v149
	ds_read_b64_tr_b16 v[136:137], v0
	v_add_u32_e32 v0, v147, v166
	s_waitcnt lgkmcnt(4)
	v_mfma_f32_32x32x16_bf16 v[50:65], v[142:145], v[66:69], v[50:65]
	v_add_u32_e32 v145, 0x12000, v148
	v_add_u32_e32 v144, 0x13000, v148
	v_add_u32_e32 v143, 0x14000, v148
	v_add_u32_e32 v142, 0x15000, v148
	v_mfma_f32_32x32x16_bf16 v[2:17], v[138:141], v[70:73], v[2:17]
	ds_read_b64_tr_b16 v[138:139], v0
	v_add_u32_e32 v0, v146, v166
	ds_read_b64_tr_b16 v[140:141], v0
	v_add_u32_e32 v0, v145, v149
	s_waitcnt lgkmcnt(4)
	v_mfma_f32_32x32x16_bf16 v[18:33], v[150:153], v[66:69], v[18:33]
	ds_read_b64_tr_b16 v[150:151], v0
	v_add_u32_e32 v0, v144, v149
	ds_read_b64_tr_b16 v[152:153], v0
	v_add_u32_e32 v0, v145, v166
	ds_read_b64_tr_b16 v[154:155], v0
	v_add_u32_e32 v0, v144, v166
	ds_read_b64_tr_b16 v[156:157], v0
	v_add_u32_e32 v0, v143, v149
	s_waitcnt lgkmcnt(6)
	v_mfma_f32_32x32x16_bf16 v[34:49], v[134:137], v[110:113], v[34:49]
	ds_read_b64_tr_b16 v[134:135], v0
	v_add_u32_e32 v0, v142, v149
	ds_read_b64_tr_b16 v[136:137], v0
	v_add_u32_e32 v0, v143, v166
	s_waitcnt lgkmcnt(4)
	v_mfma_f32_32x32x16_bf16 v[50:65], v[150:153], v[106:109], v[50:65]
	ds_read_b64_tr_b16 v[150:151], v0
	v_add_u32_e32 v0, v142, v166
	ds_read_b64_tr_b16 v[152:153], v0
	v_mfma_f32_32x32x16_bf16 v[2:17], v[138:141], v[110:113], v[2:17]
	v_add_u32_e32 v141, 0x16000, v148
	v_add_u32_e32 v140, 0x17000, v148
	v_add_u32_e32 v0, v141, v149
	v_add_u32_e32 v139, 0x18000, v148
	v_add_u32_e32 v138, 0x19000, v148
	s_waitcnt lgkmcnt(4)
	v_mfma_f32_32x32x16_bf16 v[18:33], v[154:157], v[106:109], v[18:33]
	ds_read_b64_tr_b16 v[154:155], v0
	v_add_u32_e32 v0, v140, v149
	ds_read_b64_tr_b16 v[156:157], v0
	v_add_u32_e32 v0, v141, v166
	ds_read_b64_tr_b16 v[158:159], v0
	v_add_u32_e32 v0, v140, v166
	ds_read_b64_tr_b16 v[160:161], v0
	v_add_u32_e32 v0, v139, v149
	s_waitcnt lgkmcnt(4)
	v_mfma_f32_32x32x16_bf16 v[2:17], v[150:153], v[102:105], v[2:17]
	ds_read_b64_tr_b16 v[150:151], v0
	v_add_u32_e32 v0, v138, v149
	ds_read_b64_tr_b16 v[152:153], v0
	v_add_u32_e32 v0, v139, v166
	v_mfma_f32_32x32x16_bf16 v[34:49], v[134:137], v[102:105], v[34:49]
	v_add_u32_e32 v137, 0x1a000, v148
	v_add_u32_e32 v136, 0x1b000, v148
	v_add_u32_e32 v135, 0x1c000, v148
	v_add_u32_e32 v134, 0x1d000, v148
	s_waitcnt lgkmcnt(4)
	v_mfma_f32_32x32x16_bf16 v[50:65], v[154:157], v[98:101], v[50:65]
	ds_read_b64_tr_b16 v[154:155], v0
	v_add_u32_e32 v0, v138, v166
	ds_read_b64_tr_b16 v[156:157], v0
	v_add_u32_e32 v0, v137, v149
	s_waitcnt lgkmcnt(4)
	v_mfma_f32_32x32x16_bf16 v[18:33], v[158:161], v[98:101], v[18:33]
	ds_read_b64_tr_b16 v[158:159], v0
	v_add_u32_e32 v0, v136, v149
	ds_read_b64_tr_b16 v[160:161], v0
	v_add_u32_e32 v0, v137, v166
	ds_read_b64_tr_b16 v[162:163], v0
	s_waitcnt lgkmcnt(1)
	v_mfma_f32_32x32x16_bf16 v[50:65], v[158:161], v[82:85], v[50:65]
	v_add_u32_e32 v158, v131, v149
	ds_read_b64_tr_b16 v[158:159], v158
	v_add_u32_e32 v0, v136, v166
	ds_read_b64_tr_b16 v[164:165], v0
	v_add_u32_e32 v0, v135, v149
	s_waitcnt lgkmcnt(0)
	v_mfma_f32_32x32x16_bf16 v[18:33], v[162:165], v[82:85], v[18:33]
	v_add_u32_e32 v162, v131, v166
	ds_read_b64_tr_b16 v[162:163], v162
	v_mfma_f32_32x32x16_bf16 v[34:49], v[150:153], v[86:89], v[34:49]
	ds_read_b64_tr_b16 v[150:151], v0
	v_add_u32_e32 v0, v134, v149
	ds_read_b64_tr_b16 v[152:153], v0
	v_add_u32_e32 v0, v135, v166
	v_mfma_f32_32x32x16_bf16 v[2:17], v[154:157], v[86:89], v[2:17]
	ds_read_b64_tr_b16 v[154:155], v0
	v_add_u32_e32 v0, v134, v166
	ds_read_b64_tr_b16 v[156:157], v0
	v_add_u32_e32 v0, 0x1f000, v148
	v_add_u32_e32 v160, v0, v149
	v_add_u32_e32 v164, v0, v166
	ds_read_b64_tr_b16 v[160:161], v160
	ds_read_b64_tr_b16 v[164:165], v164
	s_waitcnt lgkmcnt(4)
	v_mfma_f32_32x32x16_bf16 v[34:49], v[150:153], v[78:81], v[34:49]
	v_xor_b32_e32 v166, 0x80, v149
	v_add_u32_e32 v167, v148, v166
	s_waitcnt lgkmcnt(1)
	v_mfma_f32_32x32x16_bf16 v[50:65], v[158:161], v[74:77], v[50:65]
	v_mfma_f32_32x32x16_bf16 v[2:17], v[154:157], v[78:81], v[2:17]
	s_nop 10
	v_add_f32_e64 v36, v36, v52
	v_add_f32_e64 v37, v37, v53
	v_add_f32_e64 v34, v34, v50
	v_add_f32_e64 v35, v35, v51
	v_add_f32_e64 v40, v40, v56
	v_add_f32_e64 v41, v41, v57
	v_pk_add_f32 v[38:39], v[38:39], v[54:55]
	v_pk_mul_f32 v[34:35], v[130:131], v[34:35] op_sel_hi:[0,1]
	v_pk_mul_f32 v[36:37], v[130:131], v[36:37] op_sel_hi:[0,1]
	v_cvt_pk_bf16_f32 v34, v34, v35
	s_waitcnt lgkmcnt(0)
	v_mfma_f32_32x32x16_bf16 v[18:33], v[162:165], v[74:77], v[18:33]
	v_cvt_pk_bf16_f32 v35, v36, v37
	v_mul_f32_e64 v36, v130, v38
	v_mul_f32_e64 v37, v130, v39
	v_mul_f32_e64 v38, v130, v40
	v_mul_f32_e64 v39, v130, v41
	v_cvt_pk_bf16_f32 v36, v36, v37
	v_cvt_pk_bf16_f32 v37, v38, v39
	v_pk_add_f32 v[44:45], v[44:45], v[60:61]
	v_pk_add_f32 v[42:43], v[42:43], v[58:59]
	s_nop 2
	v_pk_add_f32 v[4:5], v[4:5], v[20:21]
	v_pk_add_f32 v[2:3], v[2:3], v[18:19]
	v_pk_add_f32 v[8:9], v[8:9], v[24:25]
	v_pk_add_f32 v[6:7], v[6:7], v[22:23]
	v_pk_mul_f32 v[2:3], v[130:131], v[2:3] op_sel_hi:[0,1]
	v_pk_mul_f32 v[4:5], v[130:131], v[4:5] op_sel_hi:[0,1]
	v_cvt_pk_bf16_f32 v2, v2, v3
	v_cvt_pk_bf16_f32 v3, v4, v5
	v_pk_mul_f32 v[4:5], v[130:131], v[6:7] op_sel_hi:[0,1]
	v_pk_mul_f32 v[6:7], v[130:131], v[8:9] op_sel_hi:[0,1]
	v_cvt_pk_bf16_f32 v4, v4, v5
	v_cvt_pk_bf16_f32 v5, v6, v7
	v_permlane32_swap_b32_e32 v34, v36
	v_permlane32_swap_b32_e32 v35, v37
	v_pk_add_f32 v[12:13], v[12:13], v[28:29]
	v_pk_add_f32 v[10:11], v[10:11], v[26:27]
	v_permlane32_swap_b32_e32 v2, v4
	v_permlane32_swap_b32_e32 v3, v5
	v_pk_add_f32 v[48:49], v[48:49], v[64:65]
	v_pk_add_f32 v[46:47], v[46:47], v[62:63]
	global_store_dwordx4 v[132:133], v[34:37], off
	v_pk_add_f32 v[16:17], v[16:17], v[32:33]
	v_pk_add_f32 v[14:15], v[14:15], v[30:31]
	v_pk_mul_f32 v[34:35], v[130:131], v[42:43] op_sel_hi:[0,1]
	v_pk_mul_f32 v[36:37], v[130:131], v[44:45] op_sel_hi:[0,1]
	global_store_dwordx4 v[132:133], v[2:5], off offset:64
	v_cvt_pk_bf16_f32 v34, v34, v35
	v_cvt_pk_bf16_f32 v35, v36, v37
	v_pk_mul_f32 v[2:3], v[130:131], v[10:11] op_sel_hi:[0,1]
	v_pk_mul_f32 v[4:5], v[130:131], v[12:13] op_sel_hi:[0,1]
	v_pk_mul_f32 v[36:37], v[130:131], v[46:47] op_sel_hi:[0,1]
	v_pk_mul_f32 v[38:39], v[130:131], v[48:49] op_sel_hi:[0,1]
	v_cvt_pk_bf16_f32 v2, v2, v3
	v_cvt_pk_bf16_f32 v3, v4, v5
	v_pk_mul_f32 v[4:5], v[130:131], v[14:15] op_sel_hi:[0,1]
	v_pk_mul_f32 v[6:7], v[130:131], v[16:17] op_sel_hi:[0,1]
	v_cvt_pk_bf16_f32 v36, v36, v37
	v_cvt_pk_bf16_f32 v37, v38, v39
	v_cvt_pk_bf16_f32 v4, v4, v5
	v_cvt_pk_bf16_f32 v5, v6, v7
	v_permlane32_swap_b32_e32 v34, v36
	v_permlane32_swap_b32_e32 v35, v37
	v_permlane32_swap_b32_e32 v2, v4
	v_permlane32_swap_b32_e32 v3, v5
	global_store_dwordx4 v[132:133], v[34:37], off offset:32
	global_store_dwordx4 v[132:133], v[2:5], off offset:96
	ds_read_b64_tr_b16 v[2:3], v167
	ds_read_b64_tr_b16 v[4:5], v167 offset:4096
	ds_read_b64_tr_b16 v[6:7], v169
	ds_read_b64_tr_b16 v[8:9], v169 offset:4096
	ds_read_b64_tr_b16 v[10:11], v167 offset:8192
	ds_read_b64_tr_b16 v[12:13], v167 offset:12288
	ds_read_b64_tr_b16 v[18:19], v169 offset:8192
	ds_read_b64_tr_b16 v[20:21], v169 offset:12288
	s_waitcnt lgkmcnt(6)
	v_mfma_f32_32x32x16_bf16 v[34:49], v[2:5], v[126:129], 0
	ds_read_b64_tr_b16 v[150:151], v167 offset:16384
	ds_read_b64_tr_b16 v[152:153], v167 offset:20480
	ds_read_b64_tr_b16 v[154:155], v169 offset:16384
	ds_read_b64_tr_b16 v[156:157], v169 offset:20480
	ds_read_b64_tr_b16 v[158:159], v167 offset:24576
	ds_read_b64_tr_b16 v[160:161], v167 offset:28672
	ds_read_b64_tr_b16 v[162:163], v169 offset:24576
	ds_read_b64_tr_b16 v[164:165], v169 offset:28672
	s_waitcnt lgkmcnt(10)
	v_mfma_f32_32x32x16_bf16 v[50:65], v[10:13], v[122:125], 0
	v_mfma_f32_32x32x16_bf16 v[2:17], v[6:9], v[126:129], 0
	s_waitcnt lgkmcnt(8)
	v_mfma_f32_32x32x16_bf16 v[18:33], v[18:21], v[122:125], 0
	s_waitcnt lgkmcnt(6)
	v_mfma_f32_32x32x16_bf16 v[34:49], v[150:153], v[118:121], v[34:49]
	s_waitcnt lgkmcnt(2)
	v_mfma_f32_32x32x16_bf16 v[50:65], v[158:161], v[114:117], v[50:65]
	v_mfma_f32_32x32x16_bf16 v[2:17], v[154:157], v[118:121], v[2:17]
	s_waitcnt lgkmcnt(0)
	v_mfma_f32_32x32x16_bf16 v[18:33], v[162:165], v[114:117], v[18:33]
	ds_read_b64_tr_b16 v[150:151], v167 offset:32768
	ds_read_b64_tr_b16 v[152:153], v167 offset:36864
	ds_read_b64_tr_b16 v[154:155], v169 offset:32768
	ds_read_b64_tr_b16 v[156:157], v169 offset:36864
	ds_read_b64_tr_b16 v[158:159], v167 offset:40960
	ds_read_b64_tr_b16 v[160:161], v167 offset:45056
	ds_read_b64_tr_b16 v[162:163], v169 offset:40960
	ds_read_b64_tr_b16 v[164:165], v169 offset:45056
	s_waitcnt lgkmcnt(6)
	v_mfma_f32_32x32x16_bf16 v[34:49], v[150:153], v[94:97], v[34:49]
	s_waitcnt lgkmcnt(2)
	v_mfma_f32_32x32x16_bf16 v[50:65], v[158:161], v[90:93], v[50:65]
	v_mfma_f32_32x32x16_bf16 v[2:17], v[154:157], v[94:97], v[2:17]
	s_waitcnt lgkmcnt(0)
	v_mfma_f32_32x32x16_bf16 v[18:33], v[162:165], v[90:93], v[18:33]
	ds_read_b64_tr_b16 v[150:151], v167 offset:49152
	ds_read_b64_tr_b16 v[152:153], v167 offset:53248
	ds_read_b64_tr_b16 v[154:155], v169 offset:49152
	ds_read_b64_tr_b16 v[156:157], v169 offset:53248
	ds_read_b64_tr_b16 v[158:159], v167 offset:57344
	ds_read_b64_tr_b16 v[160:161], v167 offset:61440
	ds_read_b64_tr_b16 v[162:163], v169 offset:57344
	ds_read_b64_tr_b16 v[164:165], v169 offset:61440
	s_waitcnt lgkmcnt(6)
	v_mfma_f32_32x32x16_bf16 v[34:49], v[150:153], v[70:73], v[34:49]
	v_add_u32_e32 v150, v147, v166
	v_add_u32_e32 v152, v146, v166
	ds_read_b64_tr_b16 v[150:151], v150
	ds_read_b64_tr_b16 v[152:153], v152
	s_waitcnt lgkmcnt(4)
	v_mfma_f32_32x32x16_bf16 v[50:65], v[158:161], v[66:69], v[50:65]
	v_add_u32_e32 v158, v145, v166
	v_add_u32_e32 v160, v144, v166
	ds_read_b64_tr_b16 v[158:159], v158
	ds_read_b64_tr_b16 v[160:161], v160
	v_mfma_f32_32x32x16_bf16 v[2:17], v[154:157], v[70:73], v[2:17]
	v_add_u32_e32 v154, v147, v168
	v_add_u32_e32 v156, v146, v168
	ds_read_b64_tr_b16 v[154:155], v154
	ds_read_b64_tr_b16 v[156:157], v156
	s_waitcnt lgkmcnt(6)
	v_mfma_f32_32x32x16_bf16 v[18:33], v[162:165], v[66:69], v[18:33]
	v_add_u32_e32 v162, v145, v168
	v_add_u32_e32 v164, v144, v168
	ds_read_b64_tr_b16 v[162:163], v162
	ds_read_b64_tr_b16 v[164:165], v164
	s_waitcnt lgkmcnt(6)
	v_mfma_f32_32x32x16_bf16 v[34:49], v[150:153], v[110:113], v[34:49]
	v_add_u32_e32 v150, v143, v166
	v_add_u32_e32 v152, v142, v166
	ds_read_b64_tr_b16 v[150:151], v150
	ds_read_b64_tr_b16 v[152:153], v152
	s_waitcnt lgkmcnt(6)
	v_mfma_f32_32x32x16_bf16 v[50:65], v[158:161], v[106:109], v[50:65]
	v_add_u32_e32 v158, v141, v166
	v_add_u32_e32 v160, v140, v166
	ds_read_b64_tr_b16 v[158:159], v158
	ds_read_b64_tr_b16 v[160:161], v160
	s_waitcnt lgkmcnt(6)
	v_mfma_f32_32x32x16_bf16 v[2:17], v[154:157], v[110:113], v[2:17]
	v_add_u32_e32 v154, v143, v168
	v_add_u32_e32 v156, v142, v168
	ds_read_b64_tr_b16 v[154:155], v154
	ds_read_b64_tr_b16 v[156:157], v156
	s_waitcnt lgkmcnt(6)
	v_mfma_f32_32x32x16_bf16 v[18:33], v[162:165], v[106:109], v[18:33]
	v_add_u32_e32 v162, v141, v168
	v_add_u32_e32 v164, v140, v168
	ds_read_b64_tr_b16 v[162:163], v162
	ds_read_b64_tr_b16 v[164:165], v164
	s_waitcnt lgkmcnt(6)
	v_mfma_f32_32x32x16_bf16 v[34:49], v[150:153], v[102:105], v[34:49]
	v_add_u32_e32 v150, v139, v166
	v_add_u32_e32 v152, v138, v166
	ds_read_b64_tr_b16 v[150:151], v150
	ds_read_b64_tr_b16 v[152:153], v152
	s_waitcnt lgkmcnt(6)
	v_mfma_f32_32x32x16_bf16 v[50:65], v[158:161], v[98:101], v[50:65]
	v_add_u32_e32 v158, v137, v166
	v_add_u32_e32 v160, v136, v166
	ds_read_b64_tr_b16 v[158:159], v158
	ds_read_b64_tr_b16 v[160:161], v160
	s_waitcnt lgkmcnt(6)
	v_mfma_f32_32x32x16_bf16 v[2:17], v[154:157], v[102:105], v[2:17]
	v_add_u32_e32 v154, v139, v168
	v_add_u32_e32 v156, v138, v168
	ds_read_b64_tr_b16 v[154:155], v154
	ds_read_b64_tr_b16 v[156:157], v156
	s_waitcnt lgkmcnt(6)
	v_mfma_f32_32x32x16_bf16 v[18:33], v[162:165], v[98:101], v[18:33]
	v_add_u32_e32 v162, v137, v168
	v_add_u32_e32 v164, v136, v168
	ds_read_b64_tr_b16 v[162:163], v162
	ds_read_b64_tr_b16 v[164:165], v164
	s_waitcnt lgkmcnt(6)
	v_mfma_f32_32x32x16_bf16 v[34:49], v[150:153], v[86:89], v[34:49]
	v_add_u32_e32 v150, v135, v166
	v_add_u32_e32 v152, v134, v166
	ds_read_b64_tr_b16 v[150:151], v150
	ds_read_b64_tr_b16 v[152:153], v152
	s_waitcnt lgkmcnt(6)
	v_mfma_f32_32x32x16_bf16 v[50:65], v[158:161], v[82:85], v[50:65]
	v_add_u32_e32 v158, v131, v166
	v_add_u32_e32 v160, v0, v166
	ds_read_b64_tr_b16 v[158:159], v158
	ds_read_b64_tr_b16 v[160:161], v160
	v_xor_b32_e32 v166, 0x100, v149
	v_add_u32_e32 v167, v148, v166
	s_waitcnt lgkmcnt(6)
	v_mfma_f32_32x32x16_bf16 v[2:17], v[154:157], v[86:89], v[2:17]
	v_add_u32_e32 v154, v135, v168
	v_add_u32_e32 v156, v134, v168
	ds_read_b64_tr_b16 v[154:155], v154
	ds_read_b64_tr_b16 v[156:157], v156
	s_waitcnt lgkmcnt(6)
	v_mfma_f32_32x32x16_bf16 v[18:33], v[162:165], v[82:85], v[18:33]
	v_add_u32_e32 v162, v131, v168
	v_add_u32_e32 v164, v0, v168
	ds_read_b64_tr_b16 v[162:163], v162
	ds_read_b64_tr_b16 v[164:165], v164
	v_xor_b32_e32 v168, 0x140, v149
	v_add_u32_e32 v169, v148, v168
	s_waitcnt lgkmcnt(6)
	v_mfma_f32_32x32x16_bf16 v[34:49], v[150:153], v[78:81], v[34:49]
	s_waitcnt lgkmcnt(4)
	v_mfma_f32_32x32x16_bf16 v[50:65], v[158:161], v[74:77], v[50:65]
	s_waitcnt lgkmcnt(2)
	v_mfma_f32_32x32x16_bf16 v[2:17], v[154:157], v[78:81], v[2:17]
	s_nop 9
	v_add_f32_e64 v36, v36, v52
	v_add_f32_e64 v37, v37, v53
	v_add_f32_e64 v34, v34, v50
	v_add_f32_e64 v35, v35, v51
	v_add_f32_e64 v40, v40, v56
	v_add_f32_e64 v41, v41, v57
	v_pk_add_f32 v[38:39], v[38:39], v[54:55]
	v_pk_mul_f32 v[34:35], v[130:131], v[34:35] op_sel_hi:[0,1]
	v_pk_mul_f32 v[36:37], v[130:131], v[36:37] op_sel_hi:[0,1]
	v_cvt_pk_bf16_f32 v34, v34, v35
	s_waitcnt lgkmcnt(0)
	v_mfma_f32_32x32x16_bf16 v[18:33], v[162:165], v[74:77], v[18:33]
	v_cvt_pk_bf16_f32 v35, v36, v37
	v_mul_f32_e64 v36, v130, v38
	v_mul_f32_e64 v37, v130, v39
	v_mul_f32_e64 v38, v130, v40
	v_mul_f32_e64 v39, v130, v41
	v_cvt_pk_bf16_f32 v36, v36, v37
	v_cvt_pk_bf16_f32 v37, v38, v39
	v_pk_add_f32 v[44:45], v[44:45], v[60:61]
	v_pk_add_f32 v[42:43], v[42:43], v[58:59]
	s_nop 2
	v_pk_add_f32 v[4:5], v[4:5], v[20:21]
	v_pk_add_f32 v[2:3], v[2:3], v[18:19]
	v_pk_add_f32 v[8:9], v[8:9], v[24:25]
	v_pk_add_f32 v[6:7], v[6:7], v[22:23]
	v_pk_mul_f32 v[2:3], v[130:131], v[2:3] op_sel_hi:[0,1]
	v_pk_mul_f32 v[4:5], v[130:131], v[4:5] op_sel_hi:[0,1]
	v_cvt_pk_bf16_f32 v2, v2, v3
	v_cvt_pk_bf16_f32 v3, v4, v5
	v_pk_mul_f32 v[4:5], v[130:131], v[6:7] op_sel_hi:[0,1]
	v_pk_mul_f32 v[6:7], v[130:131], v[8:9] op_sel_hi:[0,1]
	v_cvt_pk_bf16_f32 v4, v4, v5
	v_cvt_pk_bf16_f32 v5, v6, v7
	v_permlane32_swap_b32_e32 v34, v36
	v_permlane32_swap_b32_e32 v35, v37
	v_pk_add_f32 v[12:13], v[12:13], v[28:29]
	v_pk_add_f32 v[10:11], v[10:11], v[26:27]
	v_permlane32_swap_b32_e32 v2, v4
	v_permlane32_swap_b32_e32 v3, v5
	v_pk_add_f32 v[48:49], v[48:49], v[64:65]
	v_pk_add_f32 v[46:47], v[46:47], v[62:63]
	global_store_dwordx4 v[132:133], v[34:37], off offset:128
	v_pk_add_f32 v[16:17], v[16:17], v[32:33]
	v_pk_add_f32 v[14:15], v[14:15], v[30:31]
	v_pk_mul_f32 v[34:35], v[130:131], v[42:43] op_sel_hi:[0,1]
	v_pk_mul_f32 v[36:37], v[130:131], v[44:45] op_sel_hi:[0,1]
	global_store_dwordx4 v[132:133], v[2:5], off offset:192
	v_cvt_pk_bf16_f32 v34, v34, v35
	v_cvt_pk_bf16_f32 v35, v36, v37
	v_pk_mul_f32 v[2:3], v[130:131], v[10:11] op_sel_hi:[0,1]
	v_pk_mul_f32 v[4:5], v[130:131], v[12:13] op_sel_hi:[0,1]
	v_pk_mul_f32 v[36:37], v[130:131], v[46:47] op_sel_hi:[0,1]
	v_pk_mul_f32 v[38:39], v[130:131], v[48:49] op_sel_hi:[0,1]
	v_cvt_pk_bf16_f32 v2, v2, v3
	v_cvt_pk_bf16_f32 v3, v4, v5
	v_pk_mul_f32 v[4:5], v[130:131], v[14:15] op_sel_hi:[0,1]
	v_pk_mul_f32 v[6:7], v[130:131], v[16:17] op_sel_hi:[0,1]
	v_cvt_pk_bf16_f32 v36, v36, v37
	v_cvt_pk_bf16_f32 v37, v38, v39
	v_cvt_pk_bf16_f32 v4, v4, v5
	v_cvt_pk_bf16_f32 v5, v6, v7
	v_permlane32_swap_b32_e32 v34, v36
	v_permlane32_swap_b32_e32 v35, v37
	v_permlane32_swap_b32_e32 v2, v4
	v_permlane32_swap_b32_e32 v3, v5
	global_store_dwordx4 v[132:133], v[34:37], off offset:160
	global_store_dwordx4 v[132:133], v[2:5], off offset:224
	ds_read_b64_tr_b16 v[2:3], v167
	ds_read_b64_tr_b16 v[4:5], v167 offset:4096
	ds_read_b64_tr_b16 v[6:7], v169
	ds_read_b64_tr_b16 v[8:9], v169 offset:4096
	ds_read_b64_tr_b16 v[10:11], v167 offset:8192
	ds_read_b64_tr_b16 v[12:13], v167 offset:12288
	ds_read_b64_tr_b16 v[18:19], v169 offset:8192
	ds_read_b64_tr_b16 v[20:21], v169 offset:12288
	s_waitcnt lgkmcnt(6)
	v_mfma_f32_32x32x16_bf16 v[34:49], v[2:5], v[126:129], 0
	ds_read_b64_tr_b16 v[150:151], v167 offset:16384
	ds_read_b64_tr_b16 v[152:153], v167 offset:20480
	ds_read_b64_tr_b16 v[154:155], v169 offset:16384
	ds_read_b64_tr_b16 v[156:157], v169 offset:20480
	ds_read_b64_tr_b16 v[158:159], v167 offset:24576
	ds_read_b64_tr_b16 v[160:161], v167 offset:28672
	ds_read_b64_tr_b16 v[162:163], v169 offset:24576
	ds_read_b64_tr_b16 v[164:165], v169 offset:28672
	s_waitcnt lgkmcnt(10)
	v_mfma_f32_32x32x16_bf16 v[50:65], v[10:13], v[122:125], 0
	v_mfma_f32_32x32x16_bf16 v[2:17], v[6:9], v[126:129], 0
	s_waitcnt lgkmcnt(8)
	v_mfma_f32_32x32x16_bf16 v[18:33], v[18:21], v[122:125], 0
	s_waitcnt lgkmcnt(6)
	v_mfma_f32_32x32x16_bf16 v[34:49], v[150:153], v[118:121], v[34:49]
	s_waitcnt lgkmcnt(2)
	v_mfma_f32_32x32x16_bf16 v[50:65], v[158:161], v[114:117], v[50:65]
	v_mfma_f32_32x32x16_bf16 v[2:17], v[154:157], v[118:121], v[2:17]
	s_waitcnt lgkmcnt(0)
	v_mfma_f32_32x32x16_bf16 v[18:33], v[162:165], v[114:117], v[18:33]
	ds_read_b64_tr_b16 v[150:151], v167 offset:32768
	ds_read_b64_tr_b16 v[152:153], v167 offset:36864
	ds_read_b64_tr_b16 v[154:155], v169 offset:32768
	ds_read_b64_tr_b16 v[156:157], v169 offset:36864
	ds_read_b64_tr_b16 v[158:159], v167 offset:40960
	ds_read_b64_tr_b16 v[160:161], v167 offset:45056
	ds_read_b64_tr_b16 v[162:163], v169 offset:40960
	ds_read_b64_tr_b16 v[164:165], v169 offset:45056
	s_waitcnt lgkmcnt(6)
	v_mfma_f32_32x32x16_bf16 v[34:49], v[150:153], v[94:97], v[34:49]
	s_waitcnt lgkmcnt(2)
	v_mfma_f32_32x32x16_bf16 v[50:65], v[158:161], v[90:93], v[50:65]
	v_mfma_f32_32x32x16_bf16 v[2:17], v[154:157], v[94:97], v[2:17]
	s_waitcnt lgkmcnt(0)
	v_mfma_f32_32x32x16_bf16 v[18:33], v[162:165], v[90:93], v[18:33]
	ds_read_b64_tr_b16 v[150:151], v167 offset:49152
	ds_read_b64_tr_b16 v[152:153], v167 offset:53248
	ds_read_b64_tr_b16 v[154:155], v169 offset:49152
	ds_read_b64_tr_b16 v[156:157], v169 offset:53248
	ds_read_b64_tr_b16 v[158:159], v167 offset:57344
	ds_read_b64_tr_b16 v[160:161], v167 offset:61440
	ds_read_b64_tr_b16 v[162:163], v169 offset:57344
	ds_read_b64_tr_b16 v[164:165], v169 offset:61440
	s_waitcnt lgkmcnt(6)
	v_mfma_f32_32x32x16_bf16 v[34:49], v[150:153], v[70:73], v[34:49]
	v_add_u32_e32 v150, v147, v166
	v_add_u32_e32 v152, v146, v166
	ds_read_b64_tr_b16 v[150:151], v150
	ds_read_b64_tr_b16 v[152:153], v152
	s_waitcnt lgkmcnt(4)
	v_mfma_f32_32x32x16_bf16 v[50:65], v[158:161], v[66:69], v[50:65]
	v_add_u32_e32 v158, v145, v166
	v_add_u32_e32 v160, v144, v166
	ds_read_b64_tr_b16 v[158:159], v158
	ds_read_b64_tr_b16 v[160:161], v160
	v_mfma_f32_32x32x16_bf16 v[2:17], v[154:157], v[70:73], v[2:17]
	v_add_u32_e32 v154, v147, v168
	v_add_u32_e32 v156, v146, v168
	ds_read_b64_tr_b16 v[154:155], v154
	ds_read_b64_tr_b16 v[156:157], v156
	s_waitcnt lgkmcnt(6)
	v_mfma_f32_32x32x16_bf16 v[18:33], v[162:165], v[66:69], v[18:33]
	v_add_u32_e32 v162, v145, v168
	v_add_u32_e32 v164, v144, v168
	ds_read_b64_tr_b16 v[162:163], v162
	ds_read_b64_tr_b16 v[164:165], v164
	s_waitcnt lgkmcnt(6)
	v_mfma_f32_32x32x16_bf16 v[34:49], v[150:153], v[110:113], v[34:49]
	v_add_u32_e32 v150, v143, v166
	v_add_u32_e32 v152, v142, v166
	ds_read_b64_tr_b16 v[150:151], v150
	ds_read_b64_tr_b16 v[152:153], v152
	s_waitcnt lgkmcnt(6)
	v_mfma_f32_32x32x16_bf16 v[50:65], v[158:161], v[106:109], v[50:65]
	v_add_u32_e32 v158, v141, v166
	v_add_u32_e32 v160, v140, v166
	ds_read_b64_tr_b16 v[158:159], v158
	ds_read_b64_tr_b16 v[160:161], v160
	s_waitcnt lgkmcnt(6)
	v_mfma_f32_32x32x16_bf16 v[2:17], v[154:157], v[110:113], v[2:17]
	v_add_u32_e32 v154, v143, v168
	v_add_u32_e32 v156, v142, v168
	ds_read_b64_tr_b16 v[154:155], v154
	ds_read_b64_tr_b16 v[156:157], v156
	s_waitcnt lgkmcnt(6)
	v_mfma_f32_32x32x16_bf16 v[18:33], v[162:165], v[106:109], v[18:33]
	v_add_u32_e32 v162, v141, v168
	v_add_u32_e32 v164, v140, v168
	ds_read_b64_tr_b16 v[162:163], v162
	ds_read_b64_tr_b16 v[164:165], v164
	s_waitcnt lgkmcnt(6)
	v_mfma_f32_32x32x16_bf16 v[34:49], v[150:153], v[102:105], v[34:49]
	v_add_u32_e32 v150, v139, v166
	v_add_u32_e32 v152, v138, v166
	ds_read_b64_tr_b16 v[150:151], v150
	ds_read_b64_tr_b16 v[152:153], v152
	s_waitcnt lgkmcnt(6)
	v_mfma_f32_32x32x16_bf16 v[50:65], v[158:161], v[98:101], v[50:65]
	v_add_u32_e32 v158, v137, v166
	v_add_u32_e32 v160, v136, v166
	ds_read_b64_tr_b16 v[158:159], v158
	ds_read_b64_tr_b16 v[160:161], v160
	s_waitcnt lgkmcnt(6)
	v_mfma_f32_32x32x16_bf16 v[2:17], v[154:157], v[102:105], v[2:17]
	v_add_u32_e32 v154, v139, v168
	v_add_u32_e32 v156, v138, v168
	ds_read_b64_tr_b16 v[154:155], v154
	ds_read_b64_tr_b16 v[156:157], v156
	s_waitcnt lgkmcnt(6)
	v_mfma_f32_32x32x16_bf16 v[18:33], v[162:165], v[98:101], v[18:33]
	v_add_u32_e32 v162, v137, v168
	v_add_u32_e32 v164, v136, v168
	ds_read_b64_tr_b16 v[162:163], v162
	ds_read_b64_tr_b16 v[164:165], v164
	s_waitcnt lgkmcnt(6)
	v_mfma_f32_32x32x16_bf16 v[34:49], v[150:153], v[86:89], v[34:49]
	v_add_u32_e32 v150, v135, v166
	v_add_u32_e32 v152, v134, v166
	ds_read_b64_tr_b16 v[150:151], v150
	ds_read_b64_tr_b16 v[152:153], v152
	s_waitcnt lgkmcnt(6)
	v_mfma_f32_32x32x16_bf16 v[50:65], v[158:161], v[82:85], v[50:65]
	v_add_u32_e32 v158, v131, v166
	v_add_u32_e32 v160, v0, v166
	ds_read_b64_tr_b16 v[158:159], v158
	ds_read_b64_tr_b16 v[160:161], v160
	s_waitcnt lgkmcnt(6)
	v_mfma_f32_32x32x16_bf16 v[2:17], v[154:157], v[86:89], v[2:17]
	v_add_u32_e32 v154, v135, v168
	v_add_u32_e32 v156, v134, v168
	ds_read_b64_tr_b16 v[154:155], v154
	ds_read_b64_tr_b16 v[156:157], v156
	s_waitcnt lgkmcnt(6)
	v_mfma_f32_32x32x16_bf16 v[18:33], v[162:165], v[82:85], v[18:33]
	v_add_u32_e32 v162, v131, v168
	v_add_u32_e32 v164, v0, v168
	ds_read_b64_tr_b16 v[162:163], v162
	ds_read_b64_tr_b16 v[164:165], v164
	s_waitcnt lgkmcnt(6)
	v_mfma_f32_32x32x16_bf16 v[34:49], v[150:153], v[78:81], v[34:49]
	v_xor_b32_e32 v150, 0x180, v149
	v_xor_b32_e32 v149, 0x1c0, v149
	v_add_u32_e32 v151, v148, v150
	v_add_u32_e32 v148, v148, v149
	s_waitcnt lgkmcnt(4)
	v_mfma_f32_32x32x16_bf16 v[50:65], v[158:161], v[74:77], v[50:65]
	s_waitcnt lgkmcnt(2)
	v_mfma_f32_32x32x16_bf16 v[2:17], v[154:157], v[78:81], v[2:17]
	s_nop 9
	v_add_f32_e64 v36, v36, v52
	v_add_f32_e64 v37, v37, v53
	v_add_f32_e64 v34, v34, v50
	v_add_f32_e64 v35, v35, v51
	v_add_f32_e64 v40, v40, v56
	v_add_f32_e64 v41, v41, v57
	v_pk_add_f32 v[38:39], v[38:39], v[54:55]
	v_pk_mul_f32 v[34:35], v[130:131], v[34:35] op_sel_hi:[0,1]
	v_pk_mul_f32 v[36:37], v[130:131], v[36:37] op_sel_hi:[0,1]
	v_cvt_pk_bf16_f32 v34, v34, v35
	s_waitcnt lgkmcnt(0)
	v_mfma_f32_32x32x16_bf16 v[18:33], v[162:165], v[74:77], v[18:33]
	v_cvt_pk_bf16_f32 v35, v36, v37
	v_mul_f32_e64 v36, v130, v38
	v_mul_f32_e64 v37, v130, v39
	v_mul_f32_e64 v38, v130, v40
	v_mul_f32_e64 v39, v130, v41
	v_cvt_pk_bf16_f32 v36, v36, v37
	v_cvt_pk_bf16_f32 v37, v38, v39
	v_pk_add_f32 v[44:45], v[44:45], v[60:61]
	v_pk_add_f32 v[42:43], v[42:43], v[58:59]
	s_nop 2
	v_pk_add_f32 v[4:5], v[4:5], v[20:21]
	v_pk_add_f32 v[2:3], v[2:3], v[18:19]
	v_pk_add_f32 v[8:9], v[8:9], v[24:25]
	v_pk_add_f32 v[6:7], v[6:7], v[22:23]
	v_pk_mul_f32 v[2:3], v[130:131], v[2:3] op_sel_hi:[0,1]
	v_pk_mul_f32 v[4:5], v[130:131], v[4:5] op_sel_hi:[0,1]
	v_cvt_pk_bf16_f32 v2, v2, v3
	v_cvt_pk_bf16_f32 v3, v4, v5
	v_pk_mul_f32 v[4:5], v[130:131], v[6:7] op_sel_hi:[0,1]
	v_pk_mul_f32 v[6:7], v[130:131], v[8:9] op_sel_hi:[0,1]
	v_cvt_pk_bf16_f32 v4, v4, v5
	v_cvt_pk_bf16_f32 v5, v6, v7
	v_permlane32_swap_b32_e32 v34, v36
	v_permlane32_swap_b32_e32 v35, v37
	v_pk_add_f32 v[12:13], v[12:13], v[28:29]
	v_pk_add_f32 v[10:11], v[10:11], v[26:27]
	v_permlane32_swap_b32_e32 v2, v4
	v_permlane32_swap_b32_e32 v3, v5
	v_pk_add_f32 v[48:49], v[48:49], v[64:65]
	v_pk_add_f32 v[46:47], v[46:47], v[62:63]
	global_store_dwordx4 v[132:133], v[34:37], off offset:256
	v_pk_add_f32 v[16:17], v[16:17], v[32:33]
	v_pk_add_f32 v[14:15], v[14:15], v[30:31]
	v_pk_mul_f32 v[34:35], v[130:131], v[42:43] op_sel_hi:[0,1]
	v_pk_mul_f32 v[36:37], v[130:131], v[44:45] op_sel_hi:[0,1]
	global_store_dwordx4 v[132:133], v[2:5], off offset:320
	v_cvt_pk_bf16_f32 v34, v34, v35
	v_cvt_pk_bf16_f32 v35, v36, v37
	v_pk_mul_f32 v[2:3], v[130:131], v[10:11] op_sel_hi:[0,1]
	v_pk_mul_f32 v[4:5], v[130:131], v[12:13] op_sel_hi:[0,1]
	v_pk_mul_f32 v[36:37], v[130:131], v[46:47] op_sel_hi:[0,1]
	v_pk_mul_f32 v[38:39], v[130:131], v[48:49] op_sel_hi:[0,1]
	v_cvt_pk_bf16_f32 v2, v2, v3
	v_cvt_pk_bf16_f32 v3, v4, v5
	v_pk_mul_f32 v[4:5], v[130:131], v[14:15] op_sel_hi:[0,1]
	v_pk_mul_f32 v[6:7], v[130:131], v[16:17] op_sel_hi:[0,1]
	v_cvt_pk_bf16_f32 v36, v36, v37
	v_cvt_pk_bf16_f32 v37, v38, v39
	v_cvt_pk_bf16_f32 v4, v4, v5
	v_cvt_pk_bf16_f32 v5, v6, v7
	v_permlane32_swap_b32_e32 v34, v36
	v_permlane32_swap_b32_e32 v35, v37
	v_permlane32_swap_b32_e32 v2, v4
	v_permlane32_swap_b32_e32 v3, v5
	global_store_dwordx4 v[132:133], v[34:37], off offset:288
	global_store_dwordx4 v[132:133], v[2:5], off offset:352
	ds_read_b64_tr_b16 v[2:3], v151
	ds_read_b64_tr_b16 v[4:5], v151 offset:4096
	ds_read_b64_tr_b16 v[6:7], v148
	ds_read_b64_tr_b16 v[8:9], v148 offset:4096
	ds_read_b64_tr_b16 v[10:11], v151 offset:8192
	ds_read_b64_tr_b16 v[12:13], v151 offset:12288
	ds_read_b64_tr_b16 v[18:19], v148 offset:8192
	ds_read_b64_tr_b16 v[20:21], v148 offset:12288
	s_waitcnt lgkmcnt(6)
	v_mfma_f32_32x32x16_bf16 v[34:49], v[2:5], v[126:129], 0
	s_waitcnt lgkmcnt(2)
	v_mfma_f32_32x32x16_bf16 v[50:65], v[10:13], v[122:125], 0
	v_mfma_f32_32x32x16_bf16 v[2:17], v[6:9], v[126:129], 0
	s_waitcnt lgkmcnt(0)
	v_mfma_f32_32x32x16_bf16 v[18:33], v[18:21], v[122:125], 0
	ds_read_b64_tr_b16 v[126:127], v151 offset:16384
	ds_read_b64_tr_b16 v[128:129], v151 offset:20480
	ds_read_b64_tr_b16 v[152:153], v148 offset:16384
	ds_read_b64_tr_b16 v[154:155], v148 offset:20480
	ds_read_b64_tr_b16 v[156:157], v151 offset:24576
	ds_read_b64_tr_b16 v[158:159], v151 offset:28672
	ds_read_b64_tr_b16 v[122:123], v148 offset:24576
	ds_read_b64_tr_b16 v[124:125], v148 offset:28672
	s_waitcnt lgkmcnt(6)
	v_mfma_f32_32x32x16_bf16 v[34:49], v[126:129], v[118:121], v[34:49]
	s_waitcnt lgkmcnt(2)
	v_mfma_f32_32x32x16_bf16 v[50:65], v[156:159], v[114:117], v[50:65]
	v_mfma_f32_32x32x16_bf16 v[2:17], v[152:155], v[118:121], v[2:17]
	s_waitcnt lgkmcnt(0)
	v_mfma_f32_32x32x16_bf16 v[18:33], v[122:125], v[114:117], v[18:33]
	ds_read_b64_tr_b16 v[114:115], v151 offset:32768
	ds_read_b64_tr_b16 v[116:117], v151 offset:36864
	ds_read_b64_tr_b16 v[118:119], v148 offset:32768
	ds_read_b64_tr_b16 v[120:121], v148 offset:36864
	ds_read_b64_tr_b16 v[122:123], v151 offset:40960
	ds_read_b64_tr_b16 v[124:125], v151 offset:45056
	ds_read_b64_tr_b16 v[126:127], v148 offset:40960
	ds_read_b64_tr_b16 v[128:129], v148 offset:45056
	s_waitcnt lgkmcnt(6)
	v_mfma_f32_32x32x16_bf16 v[34:49], v[114:117], v[94:97], v[34:49]
	s_waitcnt lgkmcnt(2)
	v_mfma_f32_32x32x16_bf16 v[50:65], v[122:125], v[90:93], v[50:65]
	v_mfma_f32_32x32x16_bf16 v[2:17], v[118:121], v[94:97], v[2:17]
	s_waitcnt lgkmcnt(0)
	v_mfma_f32_32x32x16_bf16 v[18:33], v[126:129], v[90:93], v[18:33]
	ds_read_b64_tr_b16 v[90:91], v151 offset:49152
	ds_read_b64_tr_b16 v[92:93], v151 offset:53248
	ds_read_b64_tr_b16 v[94:95], v148 offset:49152
	ds_read_b64_tr_b16 v[96:97], v148 offset:53248
	ds_read_b64_tr_b16 v[114:115], v151 offset:57344
	ds_read_b64_tr_b16 v[116:117], v151 offset:61440
	ds_read_b64_tr_b16 v[118:119], v148 offset:57344
	ds_read_b64_tr_b16 v[120:121], v148 offset:61440
	s_waitcnt lgkmcnt(6)
	v_mfma_f32_32x32x16_bf16 v[34:49], v[90:93], v[70:73], v[34:49]
	v_add_u32_e32 v90, v145, v150
	v_add_u32_e32 v92, v144, v150
	ds_read_b64_tr_b16 v[90:91], v90
	ds_read_b64_tr_b16 v[92:93], v92
	s_waitcnt lgkmcnt(4)
	v_mfma_f32_32x32x16_bf16 v[50:65], v[114:117], v[66:69], v[50:65]
	v_mfma_f32_32x32x16_bf16 v[2:17], v[94:97], v[70:73], v[2:17]
	v_add_u32_e32 v70, v147, v149
	v_add_u32_e32 v72, v146, v149
	v_add_u32_e32 v94, v145, v149
	v_add_u32_e32 v96, v144, v149
	ds_read_b64_tr_b16 v[70:71], v70
	ds_read_b64_tr_b16 v[72:73], v72
	ds_read_b64_tr_b16 v[94:95], v94
	ds_read_b64_tr_b16 v[96:97], v96
	s_waitcnt lgkmcnt(6)
	v_mfma_f32_32x32x16_bf16 v[18:33], v[118:121], v[66:69], v[18:33]
	v_add_u32_e32 v66, v147, v150
	v_add_u32_e32 v68, v146, v150
	ds_read_b64_tr_b16 v[66:67], v66
	ds_read_b64_tr_b16 v[68:69], v68
	s_waitcnt lgkmcnt(0)
	v_mfma_f32_32x32x16_bf16 v[34:49], v[66:69], v[110:113], v[34:49]
	v_add_u32_e32 v66, v143, v150
	v_add_u32_e32 v68, v142, v150
	ds_read_b64_tr_b16 v[66:67], v66
	ds_read_b64_tr_b16 v[68:69], v68
	v_mfma_f32_32x32x16_bf16 v[50:65], v[90:93], v[106:109], v[50:65]
	v_add_u32_e32 v90, v141, v150
	v_add_u32_e32 v92, v140, v150
	ds_read_b64_tr_b16 v[90:91], v90
	ds_read_b64_tr_b16 v[92:93], v92
	v_mfma_f32_32x32x16_bf16 v[2:17], v[70:73], v[110:113], v[2:17]
	v_add_u32_e32 v70, v143, v149
	v_add_u32_e32 v72, v142, v149
	ds_read_b64_tr_b16 v[70:71], v70
	ds_read_b64_tr_b16 v[72:73], v72
	v_mfma_f32_32x32x16_bf16 v[18:33], v[94:97], v[106:109], v[18:33]
	v_add_u32_e32 v94, v141, v149
	v_add_u32_e32 v96, v140, v149
	ds_read_b64_tr_b16 v[94:95], v94
	ds_read_b64_tr_b16 v[96:97], v96
	s_waitcnt lgkmcnt(6)
	v_mfma_f32_32x32x16_bf16 v[34:49], v[66:69], v[102:105], v[34:49]
	v_add_u32_e32 v66, v139, v150
	v_add_u32_e32 v68, v138, v150
	ds_read_b64_tr_b16 v[66:67], v66
	ds_read_b64_tr_b16 v[68:69], v68
	s_waitcnt lgkmcnt(6)
	v_mfma_f32_32x32x16_bf16 v[50:65], v[90:93], v[98:101], v[50:65]
	v_add_u32_e32 v90, v137, v150
	v_add_u32_e32 v92, v136, v150
	ds_read_b64_tr_b16 v[90:91], v90
	ds_read_b64_tr_b16 v[92:93], v92
	s_waitcnt lgkmcnt(6)
	v_mfma_f32_32x32x16_bf16 v[2:17], v[70:73], v[102:105], v[2:17]
	v_add_u32_e32 v70, v139, v149
	v_add_u32_e32 v72, v138, v149
	ds_read_b64_tr_b16 v[70:71], v70
	ds_read_b64_tr_b16 v[72:73], v72
	s_waitcnt lgkmcnt(6)
	v_mfma_f32_32x32x16_bf16 v[18:33], v[94:97], v[98:101], v[18:33]
	v_add_u32_e32 v94, v137, v149
	v_add_u32_e32 v96, v136, v149
	ds_read_b64_tr_b16 v[94:95], v94
	ds_read_b64_tr_b16 v[96:97], v96
	s_waitcnt lgkmcnt(6)
	v_mfma_f32_32x32x16_bf16 v[34:49], v[66:69], v[86:89], v[34:49]
	v_add_u32_e32 v66, v135, v150
	v_add_u32_e32 v68, v134, v150
	ds_read_b64_tr_b16 v[66:67], v66
	ds_read_b64_tr_b16 v[68:69], v68
	s_waitcnt lgkmcnt(6)
	v_mfma_f32_32x32x16_bf16 v[50:65], v[90:93], v[82:85], v[50:65]
	s_waitcnt lgkmcnt(4)
	v_mfma_f32_32x32x16_bf16 v[2:17], v[70:73], v[86:89], v[2:17]
	v_add_u32_e32 v70, v135, v149
	v_add_u32_e32 v72, v134, v149
	v_add_u32_e32 v86, v131, v149
	ds_read_b64_tr_b16 v[70:71], v70
	ds_read_b64_tr_b16 v[72:73], v72
	ds_read_b64_tr_b16 v[86:87], v86
	s_waitcnt lgkmcnt(5)
	v_mfma_f32_32x32x16_bf16 v[18:33], v[94:97], v[82:85], v[18:33]
	v_add_u32_e32 v82, v131, v150
	v_add_u32_e32 v84, v0, v150
	v_add_u32_e32 v0, v0, v149
	ds_read_b64_tr_b16 v[82:83], v82
	ds_read_b64_tr_b16 v[84:85], v84
	ds_read_b64_tr_b16 v[88:89], v0
	s_waitcnt lgkmcnt(6)
	v_mfma_f32_32x32x16_bf16 v[34:49], v[66:69], v[78:81], v[34:49]
	s_waitcnt lgkmcnt(1)
	v_mfma_f32_32x32x16_bf16 v[50:65], v[82:85], v[74:77], v[50:65]
	v_mfma_f32_32x32x16_bf16 v[2:17], v[70:73], v[78:81], v[2:17]
	s_nop 10
	v_add_f32_e64 v36, v36, v52
	v_add_f32_e64 v37, v37, v53
	v_add_f32_e64 v34, v34, v50
	v_add_f32_e64 v35, v35, v51
	v_add_f32_e64 v40, v40, v56
	v_add_f32_e64 v41, v41, v57
	v_pk_add_f32 v[38:39], v[38:39], v[54:55]
	v_pk_mul_f32 v[34:35], v[130:131], v[34:35] op_sel_hi:[0,1]
	v_pk_mul_f32 v[36:37], v[130:131], v[36:37] op_sel_hi:[0,1]
	v_cvt_pk_bf16_f32 v34, v34, v35
	s_waitcnt lgkmcnt(0)
	v_mfma_f32_32x32x16_bf16 v[18:33], v[86:89], v[74:77], v[18:33]
	v_cvt_pk_bf16_f32 v35, v36, v37
	v_mul_f32_e64 v36, v130, v38
	v_mul_f32_e64 v37, v130, v39
	v_mul_f32_e64 v38, v130, v40
	v_mul_f32_e64 v39, v130, v41
	v_cvt_pk_bf16_f32 v36, v36, v37
	v_cvt_pk_bf16_f32 v37, v38, v39
	v_pk_add_f32 v[44:45], v[44:45], v[60:61]
	v_pk_add_f32 v[42:43], v[42:43], v[58:59]
	s_nop 2
	v_pk_add_f32 v[4:5], v[4:5], v[20:21]
	v_pk_add_f32 v[2:3], v[2:3], v[18:19]
	v_pk_add_f32 v[8:9], v[8:9], v[24:25]
	v_pk_add_f32 v[6:7], v[6:7], v[22:23]
	v_pk_mul_f32 v[2:3], v[130:131], v[2:3] op_sel_hi:[0,1]
	v_pk_mul_f32 v[4:5], v[130:131], v[4:5] op_sel_hi:[0,1]
	v_cvt_pk_bf16_f32 v2, v2, v3
	v_cvt_pk_bf16_f32 v3, v4, v5
	v_pk_mul_f32 v[4:5], v[130:131], v[6:7] op_sel_hi:[0,1]
	v_pk_mul_f32 v[6:7], v[130:131], v[8:9] op_sel_hi:[0,1]
	v_cvt_pk_bf16_f32 v4, v4, v5
	v_cvt_pk_bf16_f32 v5, v6, v7
	v_permlane32_swap_b32_e32 v34, v36
	v_permlane32_swap_b32_e32 v35, v37
	v_pk_add_f32 v[12:13], v[12:13], v[28:29]
	v_pk_add_f32 v[10:11], v[10:11], v[26:27]
	v_permlane32_swap_b32_e32 v2, v4
	v_permlane32_swap_b32_e32 v3, v5
	v_pk_add_f32 v[48:49], v[48:49], v[64:65]
	v_pk_add_f32 v[46:47], v[46:47], v[62:63]
	global_store_dwordx4 v[132:133], v[34:37], off offset:384
	v_pk_add_f32 v[16:17], v[16:17], v[32:33]
	v_pk_add_f32 v[14:15], v[14:15], v[30:31]
	v_pk_mul_f32 v[34:35], v[130:131], v[42:43] op_sel_hi:[0,1]
	v_pk_mul_f32 v[36:37], v[130:131], v[44:45] op_sel_hi:[0,1]
	global_store_dwordx4 v[132:133], v[2:5], off offset:448
	v_cvt_pk_bf16_f32 v34, v34, v35
	v_cvt_pk_bf16_f32 v35, v36, v37
	v_pk_mul_f32 v[2:3], v[130:131], v[10:11] op_sel_hi:[0,1]
	v_pk_mul_f32 v[4:5], v[130:131], v[12:13] op_sel_hi:[0,1]
	v_pk_mul_f32 v[36:37], v[130:131], v[46:47] op_sel_hi:[0,1]
	v_pk_mul_f32 v[38:39], v[130:131], v[48:49] op_sel_hi:[0,1]
	v_cvt_pk_bf16_f32 v2, v2, v3
	v_cvt_pk_bf16_f32 v3, v4, v5
	v_pk_mul_f32 v[4:5], v[130:131], v[14:15] op_sel_hi:[0,1]
	v_pk_mul_f32 v[6:7], v[130:131], v[16:17] op_sel_hi:[0,1]
	v_cvt_pk_bf16_f32 v36, v36, v37
	v_cvt_pk_bf16_f32 v37, v38, v39
	v_cvt_pk_bf16_f32 v4, v4, v5
	v_cvt_pk_bf16_f32 v5, v6, v7
	v_permlane32_swap_b32_e32 v34, v36
	v_permlane32_swap_b32_e32 v35, v37
	v_permlane32_swap_b32_e32 v2, v4
	v_permlane32_swap_b32_e32 v3, v5
	global_store_dwordx4 v[132:133], v[34:37], off offset:416
	global_store_dwordx4 v[132:133], v[2:5], off offset:480
	s_branch .LBB0_699
